# v69 plus a second code prefetch at the start of the final normalization pass of the P6 and P9 epilogues (spare v243/v244, accum_offset 248)
# speedup vs baseline: 1.0033x; 1.0033x over previous
.LBB0_496:
	s_or_b64 exec, exec, s[4:5]
	s_getpc_b64 s[100:101]
	v_mbcnt_lo_u32_b32 v244, -1, 0
	v_mbcnt_hi_u32_b32 v244, -1, v244
	v_lshlrev_b32_e32 v244, 7, v244
	global_load_dword v243, v244, s[100:101]
	s_add_u32 s100, s100, 0x2000
	s_addc_u32 s101, s101, 0
	global_load_dword v243, v244, s[100:101]
	v_lshl_add_u64 v[162:163], v[210:211], 2, s[28:29]
	v_add_co_u32_e32 v166, vcc, 0x4000, v162
	s_waitcnt lgkmcnt(0)
	s_barrier
	s_mov_b64 s[0:1], 0x4000
	s_waitcnt lgkmcnt(4)
	v_addc_co_u32_e32 v167, vcc, 0, v163, vcc
	v_lshl_add_u64 v[164:165], v[162:163], 0, s[0:1]
	global_load_dwordx4 v[194:197], v[166:167], off
	global_load_dwordx4 v[178:181], v[164:165], off offset:528
	global_load_dwordx4 v[200:203], v[164:165], off offset:16
	global_load_dwordx4 v[204:207], v[164:165], off offset:512
	v_lshl_add_u32 v164, v1, 5, 0
	v_add_f32_e32 v192, v222, v223
	v_add_f32_e32 v187, v220, v221
	ds_read_b128 v[220:223], v164 offset:24576
	ds_read_b64 v[208:209], v164 offset:24592
	v_mov_b32_e32 v188, 0x3a800000
	s_mov_b32 s3, 0xf800000
	s_mov_b64 s[0:1], 0x3000
	s_waitcnt lgkmcnt(1)
	v_mul_f32_e32 v213, 0x3a800000, v220
	v_mov_b32_e32 v212, v221
	v_mov_b32_e32 v189, v213
	v_pk_mul_f32 v[190:191], v[212:213], v[188:189]
	v_lshl_add_u64 v[166:167], v[162:163], 0, s[0:1]
	v_sub_f32_e32 v164, v190, v191
	v_add_f32_e32 v164, 0x3727c5ac, v164
	v_mul_f32_e32 v165, 0x4f800000, v164
	v_cmp_gt_f32_e64 s[6:7], s3, v164
	v_add_co_u32_e32 v162, vcc, 0x3000, v162
	s_nop 0
	v_cndmask_b32_e64 v168, v164, v165, s[6:7]
	v_sqrt_f32_e32 v169, v168
	v_addc_co_u32_e32 v163, vcc, 0, v163, vcc
	global_load_dwordx4 v[174:177], v[162:163], off
	s_nop 0
	global_load_dwordx4 v[162:165], v[166:167], off offset:528
	v_add_u32_e32 v170, -1, v169
	v_fma_f32 v171, -v170, v169, v168
	v_cmp_ge_f32_e32 vcc, 0, v171
	v_add_u32_e32 v171, 1, v169
	v_mov_b32_e32 v198, 0x260
	v_cndmask_b32_e32 v170, v169, v170, vcc
	v_fma_f32 v169, -v171, v169, v168
	v_cmp_lt_f32_e32 vcc, 0, v169
	v_pk_add_f32 v[184:185], v[182:183], v[184:185]
	v_add_f32_e32 v212, v213, v213
	v_cndmask_b32_e32 v169, v170, v171, vcc
	v_mul_f32_e32 v170, 0x37800000, v169
	v_cndmask_b32_e64 v169, v169, v170, s[6:7]
	v_cmp_class_f32_e32 vcc, v168, v198
	v_fmamk_f32 v159, v220, 0xba800000, v159
	v_fmac_f32_e32 v158, 0xba800000, v220
	v_cndmask_b32_e32 v186, v169, v168, vcc
	global_load_dwordx4 v[170:173], v[166:167], off offset:16
	s_nop 0
	global_load_dwordx4 v[166:169], v[166:167], off offset:512
	v_div_scale_f32 v189, s[0:1], v186, v186, 1.0
	v_rcp_f32_e32 v190, v189
	v_fmamk_f32 v153, v220, 0xba800000, v153
	v_fmamk_f32 v152, v220, 0xba800000, v152
	s_mov_b32 s8, 0x3a800000
	v_fma_f32 v182, -v189, v190, 1.0
	v_fmac_f32_e32 v190, v182, v190
	v_div_scale_f32 v182, vcc, 1.0, v186, 1.0
	v_mul_f32_e32 v183, v182, v190
	v_fma_f32 v193, -v189, v183, v182
	v_fmac_f32_e32 v183, v193, v190
	v_fma_f32 v182, -v189, v183, v182
	v_div_fmas_f32 v182, v182, v190, v183
	v_div_fixup_f32 v216, v182, v186, 1.0
	v_mul_f32_e32 v182, v216, v216
	v_mul_f32_e32 v191, v191, v216
	v_mov_b32_e32 v190, 2.0
	v_fma_f32 v193, v223, v182, v192
	v_pk_mul_f32 v[182:183], v[216:217], v[190:191] op_sel_hi:[0,1]
	s_waitcnt lgkmcnt(0)
	v_mov_b32_e32 v186, v208
	v_pk_mul_f32 v[182:183], v[186:187], v[182:183]
	v_pk_mul_f32 v[212:213], v[212:213], v[216:217] op_sel_hi:[1,0]
	v_add_f32_e32 v183, v193, v183
	v_add_f32_e32 v186, v182, v183
	v_mul_f32_e32 v182, v216, v212
	v_mul_f32_e32 v189, v222, v216
	v_mul_f32_e32 v191, v209, v182
	v_pk_mul_f32 v[158:159], v[158:159], v[216:217] op_sel_hi:[1,0]
	v_pk_mul_f32 v[152:153], v[152:153], v[216:217] op_sel_hi:[1,0]
	v_add_f32_e32 v193, v218, v219
	v_pk_fma_f32 v[226:227], v[38:39], v[158:159], v[46:47]
	v_fmamk_f32 v157, v220, 0xba800000, v157
	v_fmamk_f32 v156, v220, 0xba800000, v156
	v_fmamk_f32 v151, v220, 0xba800000, v151
	s_waitcnt vmcnt(5)
	v_pk_add_f32 v[158:159], v[200:201], 1.0 op_sel_hi:[1,0]
	v_pk_fma_f32 v[200:201], v[32:33], v[152:153], v[36:37]
	s_waitcnt vmcnt(4)
	v_pk_add_f32 v[152:153], v[204:205], 1.0 op_sel_hi:[1,0]
	v_sub_f32_e32 v204, v186, v191
	v_add_f32_e32 v205, v189, v193
	v_pk_fma_f32 v[204:205], v[184:185], v[212:213], v[204:205] neg_lo:[1,0,0] neg_hi:[1,0,0]
	v_fmac_f32_e32 v150, 0xba800000, v220
	v_pk_mul_f32 v[204:205], v[204:205], s[8:9] op_sel_hi:[1,0]
	v_fmamk_f32 v149, v220, 0xba800000, v149
	v_fma_f32 v186, -v205, v205, v204
	v_add_f32_e32 v186, 0x3727c5ac, v186
	v_mul_f32_e32 v189, 0x4f800000, v186
	v_cmp_gt_f32_e32 vcc, s3, v186
	v_fmamk_f32 v148, v220, 0xba800000, v148
	v_pk_mul_f32 v[156:157], v[156:157], v[216:217] op_sel_hi:[1,0]
	v_cndmask_b32_e32 v186, v186, v189, vcc
	v_sqrt_f32_e32 v189, v186
	v_pk_mul_f32 v[150:151], v[150:151], v[216:217] op_sel_hi:[1,0]
	v_pk_mul_f32 v[148:149], v[148:149], v[216:217] op_sel_hi:[1,0]
	v_pk_fma_f32 v[228:229], v[28:29], v[156:157], v[44:45]
	v_pk_add_f32 v[156:157], v[202:203], 1.0 op_sel_hi:[1,0]
	v_pk_fma_f32 v[202:203], v[30:31], v[150:151], v[34:35]
	v_pk_add_f32 v[150:151], v[206:207], 1.0 op_sel_hi:[1,0]
	v_pk_fma_f32 v[206:207], v[20:21], v[148:149], v[24:25]
	v_add_u32_e32 v148, -1, v189
	v_fmamk_f32 v147, v220, 0xba800000, v147
	v_fmac_f32_e32 v146, 0xba800000, v220
	v_fma_f32 v149, -v148, v189, v186
	v_pk_mul_f32 v[146:147], v[146:147], v[216:217] op_sel_hi:[1,0]
	v_cmp_ge_f32_e64 s[6:7], 0, v149
	v_add_u32_e32 v149, 1, v189
	v_pk_fma_f32 v[212:213], v[18:19], v[146:147], v[22:23]
	v_pk_add_f32 v[146:147], v[180:181], 1.0 op_sel_hi:[1,0]
	v_fma_f32 v180, -v149, v189, v186
	v_cndmask_b32_e64 v148, v189, v148, s[6:7]
	v_cmp_lt_f32_e64 s[6:7], 0, v180
	v_fmamk_f32 v161, v220, 0xba800000, v161
	v_fmamk_f32 v160, v220, 0xba800000, v160
	v_cndmask_b32_e64 v148, v148, v149, s[6:7]
	v_mul_f32_e32 v149, 0x37800000, v148
	v_cndmask_b32_e32 v148, v148, v149, vcc
	v_cmp_class_f32_e32 vcc, v186, v198
	v_pk_mul_f32 v[160:161], v[160:161], v[216:217] op_sel_hi:[1,0]
	v_add_u32_e32 v182, s26, v1
	v_cndmask_b32_e32 v180, v148, v186, vcc
	v_div_scale_f32 v181, s[0:1], v180, v180, 1.0
	v_rcp_f32_e32 v186, v181
	v_pk_add_f32 v[148:149], v[178:179], 1.0 op_sel_hi:[1,0]
	v_pk_fma_f32 v[224:225], v[40:41], v[160:161], v[48:49]
	v_fmamk_f32 v155, v220, 0xba800000, v155
	v_fma_f32 v178, -v181, v186, 1.0
	v_fmac_f32_e32 v186, v178, v186
	v_div_scale_f32 v178, vcc, 1.0, v180, 1.0
	v_mul_f32_e32 v179, v178, v186
	v_fma_f32 v199, -v181, v179, v178
	v_fmac_f32_e32 v179, v199, v186
	v_fma_f32 v178, -v181, v179, v178
	v_fmac_f32_e32 v154, 0xba800000, v220
	v_div_fmas_f32 v178, v178, v186, v179
	v_ashrrev_i32_e32 v183, 31, v182
	v_pk_mul_f32 v[154:155], v[154:155], v[216:217] op_sel_hi:[1,0]
	v_div_fixup_f32 v186, v178, v180, 1.0
	v_sub_f32_e32 v179, v225, v205
	v_sub_f32_e32 v178, v224, v205
	v_sub_f32_e32 v181, v227, v205
	v_sub_f32_e32 v180, v226, v205
	v_lshlrev_b64 v[222:223], 11, v[182:183]
	v_pk_add_f32 v[160:161], v[196:197], 1.0 op_sel_hi:[1,0]
	v_pk_add_f32 v[182:183], v[194:195], 1.0 op_sel_hi:[1,0]
	v_pk_fma_f32 v[230:231], v[26:27], v[154:155], v[42:43]
	v_pk_mul_f32 v[180:181], v[180:181], v[186:187] op_sel_hi:[1,0]
	v_pk_mul_f32 v[178:179], v[178:179], v[186:187] op_sel_hi:[1,0]
	v_lshlrev_b64 v[154:155], 1, v[210:211]
	s_waitcnt vmcnt(3)
	v_pk_fma_f32 v[210:211], v[160:161], v[178:179], v[176:177]
	v_pk_fma_f32 v[178:179], v[182:183], v[180:181], v[174:175]
	v_sub_f32_e32 v181, v229, v205
	v_sub_f32_e32 v180, v228, v205
	v_sub_f32_e32 v217, v231, v205
	v_sub_f32_e32 v216, v230, v205
	v_pk_mul_f32 v[216:217], v[216:217], v[186:187] op_sel_hi:[1,0]
	v_pk_mul_f32 v[180:181], v[180:181], v[186:187] op_sel_hi:[1,0]
	v_lshl_add_u64 v[194:195], s[84:85], 0, v[222:223]
	s_waitcnt vmcnt(1)
	v_pk_fma_f32 v[218:219], v[156:157], v[180:181], v[172:173]
	v_pk_fma_f32 v[180:181], v[158:159], v[216:217], v[170:171]
	v_cvt_pk_bf16_f32 v208, v226, v227
	v_cvt_pk_bf16_f32 v209, v224, v225
	v_lshl_add_u64 v[194:195], v[194:195], 0, v[154:155]
	v_lshl_add_u64 v[196:197], s[66:67], 0, v[222:223]
	v_cvt_pk_bf16_f32 v178, v178, v179
	v_cvt_pk_bf16_f32 v179, v210, v211
	v_cvt_pk_bf16_f32 v210, v230, v231
	v_cvt_pk_bf16_f32 v211, v228, v229
	v_cvt_pk_bf16_f32 v180, v180, v181
	v_cvt_pk_bf16_f32 v181, v218, v219
	v_lshl_add_u64 v[196:197], v[196:197], 0, v[154:155]
	global_store_dwordx4 v[194:195], v[208:211], off
	global_store_dwordx4 v[196:197], v[178:181], off
	v_or_b32_e32 v191, 16, v1
	v_lshl_add_u32 v189, v191, 5, 0
	v_cvt_pk_bf16_f32 v178, v202, v203
	v_cvt_pk_bf16_f32 v179, v200, v201
	v_sub_f32_e32 v181, v201, v205
	v_sub_f32_e32 v180, v200, v205
	v_sub_f32_e32 v201, v203, v205
	v_sub_f32_e32 v200, v202, v205
	v_pk_mul_f32 v[200:201], v[200:201], v[186:187] op_sel_hi:[1,0]
	v_pk_mul_f32 v[180:181], v[180:181], v[186:187] op_sel_hi:[1,0]
	s_waitcnt vmcnt(2)
	v_pk_fma_f32 v[200:201], v[152:153], v[200:201], v[166:167]
	v_pk_fma_f32 v[180:181], v[150:151], v[180:181], v[168:169]
	v_cvt_pk_bf16_f32 v200, v200, v201
	v_sub_f32_e32 v203, v207, v205
	v_cvt_pk_bf16_f32 v201, v180, v181
	v_cvt_pk_bf16_f32 v180, v212, v213
	v_cvt_pk_bf16_f32 v181, v206, v207
	v_sub_f32_e32 v202, v206, v205
	v_sub_f32_e32 v207, v213, v205
	v_sub_f32_e32 v206, v212, v205
	v_pk_mul_f32 v[204:205], v[206:207], v[186:187] op_sel_hi:[1,0]
	v_pk_mul_f32 v[202:203], v[202:203], v[186:187] op_sel_hi:[1,0]
	s_nop 0
	v_pk_fma_f32 v[206:207], v[146:147], v[202:203], v[164:165]
	v_pk_fma_f32 v[202:203], v[148:149], v[204:205], v[162:163]
	s_nop 0
	v_cvt_pk_bf16_f32 v202, v202, v203
	v_cvt_pk_bf16_f32 v203, v206, v207
	global_store_dwordx4 v[194:195], v[178:181], off offset:256
	global_store_dwordx4 v[196:197], v[200:203], off offset:256
	ds_read_b128 v[178:181], v189 offset:24576
	ds_read_b64 v[194:195], v189 offset:24592
	v_add_u32_e32 v202, s26, v191
	v_ashrrev_i32_e32 v203, 31, v202
	v_lshlrev_b64 v[202:203], 11, v[202:203]
	s_waitcnt lgkmcnt(1)
	v_mul_f32_e32 v197, 0x3a800000, v178
	v_mov_b32_e32 v196, v179
	v_mov_b32_e32 v189, v197
	v_pk_mul_f32 v[200:201], v[196:197], v[188:189]
	v_fmamk_f32 v145, v178, 0xba800000, v145
	v_sub_f32_e32 v179, v200, v201
	v_add_f32_e32 v179, 0x3727c5ac, v179
	v_mul_f32_e32 v186, 0x4f800000, v179
	v_cmp_gt_f32_e32 vcc, s3, v179
	v_fmamk_f32 v144, v178, 0xba800000, v144
	v_fmamk_f32 v143, v178, 0xba800000, v143
	v_cndmask_b32_e32 v179, v179, v186, vcc
	v_sqrt_f32_e32 v186, v179
	v_fmac_f32_e32 v142, 0xba800000, v178
	v_fmamk_f32 v139, v178, 0xba800000, v139
	v_fmac_f32_e32 v138, 0xba800000, v178
	v_add_u32_e32 v189, -1, v186
	v_fma_f32 v196, -v189, v186, v179
	v_cmp_ge_f32_e64 s[6:7], 0, v196
	v_add_u32_e32 v196, 1, v186
	v_fmamk_f32 v141, v178, 0xba800000, v141
	v_cndmask_b32_e64 v189, v186, v189, s[6:7]
	v_fma_f32 v186, -v196, v186, v179
	v_cmp_lt_f32_e64 s[6:7], 0, v186
	v_fmamk_f32 v140, v178, 0xba800000, v140
	v_fmamk_f32 v137, v178, 0xba800000, v137
	v_cndmask_b32_e64 v186, v189, v196, s[6:7]
	v_mul_f32_e32 v189, 0x37800000, v186
	v_cndmask_b32_e32 v186, v186, v189, vcc
	v_cmp_class_f32_e32 vcc, v179, v198
	v_fmamk_f32 v136, v178, 0xba800000, v136
	v_fmamk_f32 v135, v178, 0xba800000, v135
	v_cndmask_b32_e32 v179, v186, v179, vcc
	v_div_scale_f32 v186, s[0:1], v179, v179, 1.0
	v_rcp_f32_e32 v189, v186
	v_fmac_f32_e32 v134, 0xba800000, v178
	v_fmamk_f32 v133, v178, 0xba800000, v133
	v_fmamk_f32 v132, v178, 0xba800000, v132
	v_fma_f32 v191, -v186, v189, 1.0
	v_fmac_f32_e32 v189, v191, v189
	v_div_scale_f32 v191, vcc, 1.0, v179, 1.0
	v_mul_f32_e32 v196, v191, v189
	v_fma_f32 v199, -v186, v196, v191
	v_fmac_f32_e32 v196, v199, v189
	v_fma_f32 v186, -v186, v196, v191
	v_div_fmas_f32 v186, v186, v189, v196
	v_div_fixup_f32 v200, v186, v179, 1.0
	v_mul_f32_e32 v179, v180, v200
	v_mul_f32_e32 v180, v200, v200
	v_mul_f32_e32 v191, v201, v200
	v_fma_f32 v189, v181, v180, v192
	v_pk_mul_f32 v[180:181], v[200:201], v[190:191] op_sel_hi:[0,1]
	s_waitcnt lgkmcnt(0)
	v_mov_b32_e32 v186, v194
	v_pk_mul_f32 v[180:181], v[186:187], v[180:181]
	v_add_f32_e32 v196, v197, v197
	v_add_f32_e32 v181, v189, v181
	v_add_f32_e32 v186, v180, v181
	v_pk_mul_f32 v[180:181], v[196:197], v[200:201] op_sel_hi:[1,0]
	v_pk_mul_f32 v[142:143], v[142:143], v[200:201] op_sel_hi:[1,0]
	v_mul_f32_e32 v189, v200, v180
	v_mul_f32_e32 v189, v195, v189
	v_sub_f32_e32 v194, v186, v189
	v_add_f32_e32 v195, v179, v193
	v_pk_fma_f32 v[180:181], v[184:185], v[180:181], v[194:195] neg_lo:[1,0,0] neg_hi:[1,0,0]
	v_lshl_add_u64 v[194:195], s[84:85], 0, v[202:203]
	v_pk_mul_f32 v[180:181], v[180:181], s[8:9] op_sel_hi:[1,0]
	v_lshl_add_u64 v[204:205], v[194:195], 0, v[154:155]
	v_fma_f32 v179, -v181, v181, v180
	v_add_f32_e32 v179, 0x3727c5ac, v179
	v_mul_f32_e32 v180, 0x4f800000, v179
	v_cmp_gt_f32_e32 vcc, s3, v179
	v_lshl_add_u64 v[194:195], s[66:67], 0, v[202:203]
	v_lshl_add_u64 v[202:203], v[194:195], 0, v[154:155]
	v_cndmask_b32_e32 v179, v179, v180, vcc
	v_sqrt_f32_e32 v180, v179
	v_pk_mul_f32 v[144:145], v[144:145], v[200:201] op_sel_hi:[1,0]
	v_pk_mul_f32 v[138:139], v[138:139], v[200:201] op_sel_hi:[1,0]
	v_pk_fma_f32 v[144:145], v[40:41], v[144:145], v[48:49]
	v_add_u32_e32 v186, -1, v180
	v_fma_f32 v189, -v186, v180, v179
	v_cmp_ge_f32_e64 s[6:7], 0, v189
	v_add_u32_e32 v189, 1, v180
	v_pk_fma_f32 v[138:139], v[26:27], v[138:139], v[42:43]
	v_cndmask_b32_e64 v186, v180, v186, s[6:7]
	v_fma_f32 v180, -v189, v180, v179
	v_cmp_lt_f32_e64 s[6:7], 0, v180
	v_pk_mul_f32 v[140:141], v[140:141], v[200:201] op_sel_hi:[1,0]
	v_pk_mul_f32 v[134:135], v[134:135], v[200:201] op_sel_hi:[1,0]
	v_cndmask_b32_e64 v180, v186, v189, s[6:7]
	v_mul_f32_e32 v186, 0x37800000, v180
	v_cndmask_b32_e32 v180, v180, v186, vcc
	v_cmp_class_f32_e32 vcc, v179, v198
	v_pk_fma_f32 v[140:141], v[28:29], v[140:141], v[44:45]
	v_pk_mul_f32 v[136:137], v[136:137], v[200:201] op_sel_hi:[1,0]
	v_cndmask_b32_e32 v179, v180, v179, vcc
	v_div_scale_f32 v180, s[0:1], v179, v179, 1.0
	v_rcp_f32_e32 v186, v180
	v_pk_fma_f32 v[136:137], v[32:33], v[136:137], v[36:37]
	v_fmamk_f32 v131, v178, 0xba800000, v131
	v_fmac_f32_e32 v130, 0xba800000, v178
	v_fma_f32 v194, -v180, v186, 1.0
	v_fmac_f32_e32 v186, v194, v186
	v_div_scale_f32 v194, vcc, 1.0, v179, 1.0
	v_mul_f32_e32 v195, v194, v186
	v_fma_f32 v196, -v180, v195, v194
	v_fmac_f32_e32 v195, v196, v186
	v_fma_f32 v180, -v180, v195, v194
	v_div_fmas_f32 v180, v180, v186, v195
	v_pk_fma_f32 v[194:195], v[38:39], v[142:143], v[46:47]
	v_div_fixup_f32 v180, v180, v179, 1.0
	v_cvt_pk_bf16_f32 v142, v194, v195
	v_cvt_pk_bf16_f32 v143, v144, v145
	v_sub_f32_e32 v145, v145, v181
	v_sub_f32_e32 v144, v144, v181
	v_sub_f32_e32 v195, v195, v181
	v_sub_f32_e32 v194, v194, v181
	v_pk_mul_f32 v[194:195], v[194:195], v[180:181] op_sel_hi:[1,0]
	v_pk_mul_f32 v[144:145], v[144:145], v[180:181] op_sel_hi:[1,0]
	v_pk_fma_f32 v[194:195], v[182:183], v[194:195], v[174:175]
	v_pk_fma_f32 v[144:145], v[160:161], v[144:145], v[176:177]
	v_cvt_pk_bf16_f32 v194, v194, v195
	v_pk_mul_f32 v[130:131], v[130:131], v[200:201] op_sel_hi:[1,0]
	v_cvt_pk_bf16_f32 v195, v144, v145
	v_cvt_pk_bf16_f32 v144, v138, v139
	v_sub_f32_e32 v139, v139, v181
	v_sub_f32_e32 v138, v138, v181
	v_pk_mul_f32 v[138:139], v[138:139], v[180:181] op_sel_hi:[1,0]
	v_cvt_pk_bf16_f32 v145, v140, v141
	v_sub_f32_e32 v141, v141, v181
	v_sub_f32_e32 v140, v140, v181
	v_pk_fma_f32 v[138:139], v[158:159], v[138:139], v[170:171]
	v_pk_mul_f32 v[140:141], v[140:141], v[180:181] op_sel_hi:[1,0]
	v_cvt_pk_bf16_f32 v196, v138, v139
	v_pk_fma_f32 v[138:139], v[30:31], v[134:135], v[34:35]
	v_pk_fma_f32 v[140:141], v[156:157], v[140:141], v[172:173]
	v_pk_mul_f32 v[132:133], v[132:133], v[200:201] op_sel_hi:[1,0]
	v_cvt_pk_bf16_f32 v197, v140, v141
	global_store_dwordx4 v[204:205], v[142:145], off
	global_store_dwordx4 v[202:203], v[194:197], off
	v_cvt_pk_bf16_f32 v134, v138, v139
	v_cvt_pk_bf16_f32 v135, v136, v137
	v_sub_f32_e32 v137, v137, v181
	v_sub_f32_e32 v136, v136, v181
	v_sub_f32_e32 v139, v139, v181
	v_sub_f32_e32 v138, v138, v181
	v_pk_mul_f32 v[138:139], v[138:139], v[180:181] op_sel_hi:[1,0]
	v_pk_mul_f32 v[136:137], v[136:137], v[180:181] op_sel_hi:[1,0]
	v_pk_fma_f32 v[138:139], v[152:153], v[138:139], v[166:167]
	v_pk_fma_f32 v[136:137], v[150:151], v[136:137], v[168:169]
	v_pk_fma_f32 v[132:133], v[20:21], v[132:133], v[24:25]
	v_pk_fma_f32 v[130:131], v[18:19], v[130:131], v[22:23]
	v_cvt_pk_bf16_f32 v138, v138, v139
	v_cvt_pk_bf16_f32 v139, v136, v137
	v_or_b32_e32 v191, 32, v1
	v_cvt_pk_bf16_f32 v136, v130, v131
	v_cvt_pk_bf16_f32 v137, v132, v133
	v_sub_f32_e32 v133, v133, v181
	v_sub_f32_e32 v132, v132, v181
	v_sub_f32_e32 v131, v131, v181
	v_sub_f32_e32 v130, v130, v181
	v_pk_mul_f32 v[130:131], v[130:131], v[180:181] op_sel_hi:[1,0]
	v_pk_mul_f32 v[132:133], v[132:133], v[180:181] op_sel_hi:[1,0]
	v_pk_fma_f32 v[130:131], v[148:149], v[130:131], v[162:163]
	v_pk_fma_f32 v[132:133], v[146:147], v[132:133], v[164:165]
	v_cvt_pk_bf16_f32 v140, v130, v131
	v_lshl_add_u32 v189, v191, 5, 0
	v_cvt_pk_bf16_f32 v141, v132, v133
	global_store_dwordx4 v[204:205], v[134:137], off offset:256
	global_store_dwordx4 v[202:203], v[138:141], off offset:256
	ds_read_b128 v[130:133], v189 offset:24576
	ds_read_b64 v[134:135], v189 offset:24592
	s_waitcnt lgkmcnt(1)
	v_mul_f32_e32 v137, 0x3a800000, v130
	v_mov_b32_e32 v136, v131
	v_mov_b32_e32 v189, v137
	v_pk_mul_f32 v[138:139], v[136:137], v[188:189]
	s_waitcnt lgkmcnt(0)
	v_mov_b32_e32 v186, v134
	v_sub_f32_e32 v131, v138, v139
	v_add_f32_e32 v131, 0x3727c5ac, v131
	v_mul_f32_e32 v136, 0x4f800000, v131
	v_cmp_gt_f32_e32 vcc, s3, v131
	v_fmamk_f32 v129, v130, 0xba800000, v129
	v_fmamk_f32 v128, v130, 0xba800000, v128
	v_cndmask_b32_e32 v131, v131, v136, vcc
	v_sqrt_f32_e32 v136, v131
	v_fmamk_f32 v127, v130, 0xba800000, v127
	v_fmac_f32_e32 v126, 0xba800000, v130
	v_fmamk_f32 v123, v130, 0xba800000, v123
	v_add_u32_e32 v138, -1, v136
	v_fma_f32 v140, -v138, v136, v131
	v_cmp_ge_f32_e64 s[6:7], 0, v140
	v_add_u32_e32 v140, 1, v136
	v_fmac_f32_e32 v122, 0xba800000, v130
	v_cndmask_b32_e64 v138, v136, v138, s[6:7]
	v_fma_f32 v136, -v140, v136, v131
	v_cmp_lt_f32_e64 s[6:7], 0, v136
	v_fmamk_f32 v125, v130, 0xba800000, v125
	v_fmamk_f32 v124, v130, 0xba800000, v124
	v_cndmask_b32_e64 v136, v138, v140, s[6:7]
	v_mul_f32_e32 v138, 0x37800000, v136
	v_cndmask_b32_e32 v136, v136, v138, vcc
	v_cmp_class_f32_e32 vcc, v131, v198
	v_add_u32_e32 v140, s26, v191
	v_ashrrev_i32_e32 v141, 31, v140
	v_cndmask_b32_e32 v131, v136, v131, vcc
	v_div_scale_f32 v136, s[0:1], v131, v131, 1.0
	v_rcp_f32_e32 v138, v136
	v_lshlrev_b64 v[140:141], 11, v[140:141]
	v_fmamk_f32 v121, v130, 0xba800000, v121
	v_fmamk_f32 v120, v130, 0xba800000, v120
	v_fma_f32 v142, -v136, v138, 1.0
	v_fmac_f32_e32 v138, v142, v138
	v_div_scale_f32 v142, vcc, 1.0, v131, 1.0
	v_mul_f32_e32 v143, v142, v138
	v_fma_f32 v144, -v136, v143, v142
	v_fmac_f32_e32 v143, v144, v138
	v_fma_f32 v136, -v136, v143, v142
	v_div_fmas_f32 v136, v136, v138, v143
	v_div_fixup_f32 v138, v136, v131, 1.0
	v_mul_f32_e32 v131, v132, v138
	v_mul_f32_e32 v132, v138, v138
	v_mul_f32_e32 v191, v139, v138
	v_fma_f32 v136, v133, v132, v192
	v_pk_mul_f32 v[132:133], v[138:139], v[190:191] op_sel_hi:[0,1]
	v_pk_mul_f32 v[132:133], v[186:187], v[132:133]
	v_fmamk_f32 v119, v130, 0xba800000, v119
	v_add_f32_e32 v133, v136, v133
	v_add_f32_e32 v136, v137, v137
	v_add_f32_e32 v134, v132, v133
	v_pk_mul_f32 v[132:133], v[136:137], v[138:139] op_sel_hi:[1,0]
	v_or_b32_e32 v139, 48, v1
	v_mul_f32_e32 v136, v138, v132
	v_mul_f32_e32 v135, v135, v136
	v_sub_f32_e32 v134, v134, v135
	v_add_f32_e32 v135, v131, v193
	v_pk_fma_f32 v[132:133], v[184:185], v[132:133], v[134:135] neg_lo:[1,0,0] neg_hi:[1,0,0]
	v_pk_mul_f32 v[126:127], v[126:127], v[138:139] op_sel_hi:[1,0]
	v_pk_mul_f32 v[136:137], v[132:133], s[8:9] op_sel_hi:[1,0]
	v_pk_mul_f32 v[128:129], v[128:129], v[138:139] op_sel_hi:[1,0]
	v_fma_f32 v131, -v137, v137, v136
	v_add_f32_e32 v131, 0x3727c5ac, v131
	v_mul_f32_e32 v132, 0x4f800000, v131
	v_cmp_gt_f32_e32 vcc, s3, v131
	v_pk_fma_f32 v[128:129], v[40:41], v[128:129], v[48:49]
	v_pk_mul_f32 v[122:123], v[122:123], v[138:139] op_sel_hi:[1,0]
	v_cndmask_b32_e32 v131, v131, v132, vcc
	v_sqrt_f32_e32 v134, v131
	v_lshl_add_u64 v[132:133], s[84:85], 0, v[140:141]
	v_lshl_add_u64 v[142:143], v[132:133], 0, v[154:155]
	v_lshl_add_u64 v[132:133], s[66:67], 0, v[140:141]
	v_add_u32_e32 v135, -1, v134
	v_fma_f32 v136, -v135, v134, v131
	v_cmp_ge_f32_e64 s[6:7], 0, v136
	v_add_u32_e32 v136, 1, v134
	v_lshl_add_u64 v[140:141], v[132:133], 0, v[154:155]
	v_cndmask_b32_e64 v135, v134, v135, s[6:7]
	v_fma_f32 v134, -v136, v134, v131
	v_cmp_lt_f32_e64 s[6:7], 0, v134
	v_pk_fma_f32 v[122:123], v[26:27], v[122:123], v[42:43]
	v_pk_mul_f32 v[124:125], v[124:125], v[138:139] op_sel_hi:[1,0]
	v_cndmask_b32_e64 v134, v135, v136, s[6:7]
	v_mul_f32_e32 v135, 0x37800000, v134
	v_cndmask_b32_e32 v134, v134, v135, vcc
	v_cmp_class_f32_e32 vcc, v131, v198
	v_pk_fma_f32 v[124:125], v[28:29], v[124:125], v[44:45]
	v_fmac_f32_e32 v118, 0xba800000, v130
	v_cndmask_b32_e32 v131, v134, v131, vcc
	v_div_scale_f32 v134, s[0:1], v131, v131, 1.0
	v_rcp_f32_e32 v135, v134
	v_pk_mul_f32 v[118:119], v[118:119], v[138:139] op_sel_hi:[1,0]
	v_pk_mul_f32 v[120:121], v[120:121], v[138:139] op_sel_hi:[1,0]
	v_fmamk_f32 v117, v130, 0xba800000, v117
	v_fma_f32 v132, -v134, v135, 1.0
	v_fmac_f32_e32 v135, v132, v135
	v_div_scale_f32 v132, vcc, 1.0, v131, 1.0
	v_mul_f32_e32 v133, v132, v135
	v_fma_f32 v136, -v134, v133, v132
	v_fmac_f32_e32 v133, v136, v135
	v_fma_f32 v132, -v134, v133, v132
	v_div_fmas_f32 v132, v132, v135, v133
	v_div_fixup_f32 v136, v132, v131, 1.0
	v_pk_fma_f32 v[132:133], v[38:39], v[126:127], v[46:47]
	v_pk_fma_f32 v[120:121], v[32:33], v[120:121], v[36:37]
	v_cvt_pk_bf16_f32 v126, v132, v133
	v_cvt_pk_bf16_f32 v127, v128, v129
	v_sub_f32_e32 v129, v129, v137
	v_sub_f32_e32 v128, v128, v137
	v_sub_f32_e32 v133, v133, v137
	v_sub_f32_e32 v132, v132, v137
	v_pk_mul_f32 v[132:133], v[132:133], v[136:137] op_sel_hi:[1,0]
	v_pk_mul_f32 v[128:129], v[128:129], v[136:137] op_sel_hi:[1,0]
	v_pk_fma_f32 v[132:133], v[182:183], v[132:133], v[174:175]
	v_pk_fma_f32 v[128:129], v[160:161], v[128:129], v[176:177]
	v_cvt_pk_bf16_f32 v132, v132, v133
	v_fmamk_f32 v116, v130, 0xba800000, v116
	v_cvt_pk_bf16_f32 v133, v128, v129
	v_cvt_pk_bf16_f32 v128, v122, v123
	v_sub_f32_e32 v123, v123, v137
	v_sub_f32_e32 v122, v122, v137
	v_pk_mul_f32 v[122:123], v[122:123], v[136:137] op_sel_hi:[1,0]
	v_cvt_pk_bf16_f32 v129, v124, v125
	v_sub_f32_e32 v125, v125, v137
	v_sub_f32_e32 v124, v124, v137
	v_pk_fma_f32 v[122:123], v[158:159], v[122:123], v[170:171]
	v_pk_mul_f32 v[124:125], v[124:125], v[136:137] op_sel_hi:[1,0]
	v_cvt_pk_bf16_f32 v134, v122, v123
	v_pk_fma_f32 v[122:123], v[30:31], v[118:119], v[34:35]
	v_pk_fma_f32 v[124:125], v[156:157], v[124:125], v[172:173]
	v_fmamk_f32 v115, v130, 0xba800000, v115
	v_cvt_pk_bf16_f32 v135, v124, v125
	global_store_dwordx4 v[142:143], v[126:129], off
	global_store_dwordx4 v[140:141], v[132:135], off
	v_cvt_pk_bf16_f32 v118, v122, v123
	v_cvt_pk_bf16_f32 v119, v120, v121
	v_sub_f32_e32 v121, v121, v137
	v_sub_f32_e32 v120, v120, v137
	v_sub_f32_e32 v123, v123, v137
	v_sub_f32_e32 v122, v122, v137
	v_fmac_f32_e32 v114, 0xba800000, v130
	v_pk_mul_f32 v[122:123], v[122:123], v[136:137] op_sel_hi:[1,0]
	v_pk_mul_f32 v[120:121], v[120:121], v[136:137] op_sel_hi:[1,0]
	v_pk_mul_f32 v[114:115], v[114:115], v[138:139] op_sel_hi:[1,0]
	v_pk_mul_f32 v[116:117], v[116:117], v[138:139] op_sel_hi:[1,0]
	v_pk_fma_f32 v[120:121], v[150:151], v[120:121], v[168:169]
	v_pk_fma_f32 v[122:123], v[152:153], v[122:123], v[166:167]
	v_pk_fma_f32 v[116:117], v[20:21], v[116:117], v[24:25]
	v_pk_fma_f32 v[114:115], v[18:19], v[114:115], v[22:23]
	v_cvt_pk_bf16_f32 v122, v122, v123
	v_cvt_pk_bf16_f32 v123, v120, v121
	v_lshl_add_u32 v144, v139, 5, 0
	v_cvt_pk_bf16_f32 v120, v114, v115
	v_cvt_pk_bf16_f32 v121, v116, v117
	v_sub_f32_e32 v117, v117, v137
	v_sub_f32_e32 v116, v116, v137
	v_sub_f32_e32 v115, v115, v137
	v_sub_f32_e32 v114, v114, v137
	v_pk_mul_f32 v[114:115], v[114:115], v[136:137] op_sel_hi:[1,0]
	v_pk_mul_f32 v[116:117], v[116:117], v[136:137] op_sel_hi:[1,0]
	v_pk_fma_f32 v[114:115], v[148:149], v[114:115], v[162:163]
	v_pk_fma_f32 v[116:117], v[146:147], v[116:117], v[164:165]
	v_cvt_pk_bf16_f32 v124, v114, v115
	s_nop 0
	v_cvt_pk_bf16_f32 v125, v116, v117
	global_store_dwordx4 v[142:143], v[118:121], off offset:256
	global_store_dwordx4 v[140:141], v[122:125], off offset:256
	ds_read_b128 v[114:117], v144 offset:24576
	ds_read_b64 v[118:119], v144 offset:24592
	s_waitcnt lgkmcnt(1)
	v_mul_f32_e32 v121, 0x3a800000, v114
	v_mov_b32_e32 v120, v115
	v_mov_b32_e32 v189, v121
	v_pk_mul_f32 v[122:123], v[120:121], v[188:189]
	s_waitcnt lgkmcnt(0)
	v_mov_b32_e32 v186, v118
	v_sub_f32_e32 v115, v122, v123
	v_add_f32_e32 v115, 0x3727c5ac, v115
	v_mul_f32_e32 v120, 0x4f800000, v115
	v_cmp_gt_f32_e32 vcc, s3, v115
	v_fmamk_f32 v113, v114, 0xba800000, v113
	v_fmamk_f32 v112, v114, 0xba800000, v112
	v_cndmask_b32_e32 v115, v115, v120, vcc
	v_sqrt_f32_e32 v120, v115
	v_fmamk_f32 v111, v114, 0xba800000, v111
	v_fmac_f32_e32 v110, 0xba800000, v114
	v_fmamk_f32 v107, v114, 0xba800000, v107
	v_add_u32_e32 v122, -1, v120
	v_fma_f32 v124, -v122, v120, v115
	v_cmp_ge_f32_e64 s[6:7], 0, v124
	v_add_u32_e32 v124, 1, v120
	v_fmac_f32_e32 v106, 0xba800000, v114
	v_cndmask_b32_e64 v122, v120, v122, s[6:7]
	v_fma_f32 v120, -v124, v120, v115
	v_cmp_lt_f32_e64 s[6:7], 0, v120
	v_fmamk_f32 v109, v114, 0xba800000, v109
	v_fmamk_f32 v108, v114, 0xba800000, v108
	v_cndmask_b32_e64 v120, v122, v124, s[6:7]
	v_mul_f32_e32 v122, 0x37800000, v120
	v_cndmask_b32_e32 v120, v120, v122, vcc
	v_cmp_class_f32_e32 vcc, v115, v198
	v_add_u32_e32 v124, s26, v139
	v_ashrrev_i32_e32 v125, 31, v124
	v_cndmask_b32_e32 v115, v120, v115, vcc
	v_div_scale_f32 v120, s[0:1], v115, v115, 1.0
	v_rcp_f32_e32 v122, v120
	v_lshlrev_b64 v[124:125], 11, v[124:125]
	v_fmamk_f32 v105, v114, 0xba800000, v105
	v_fmamk_f32 v104, v114, 0xba800000, v104
	v_fma_f32 v126, -v120, v122, 1.0
	v_fmac_f32_e32 v122, v126, v122
	v_div_scale_f32 v126, vcc, 1.0, v115, 1.0
	v_mul_f32_e32 v127, v126, v122
	v_fma_f32 v128, -v120, v127, v126
	v_fmac_f32_e32 v127, v128, v122
	v_fma_f32 v120, -v120, v127, v126
	v_div_fmas_f32 v120, v120, v122, v127
	v_div_fixup_f32 v122, v120, v115, 1.0
	v_mul_f32_e32 v115, v116, v122
	v_mul_f32_e32 v116, v122, v122
	v_mul_f32_e32 v191, v123, v122
	v_fma_f32 v120, v117, v116, v192
	v_pk_mul_f32 v[116:117], v[122:123], v[190:191] op_sel_hi:[0,1]
	v_pk_mul_f32 v[116:117], v[186:187], v[116:117]
	v_fmamk_f32 v103, v114, 0xba800000, v103
	v_add_f32_e32 v117, v120, v117
	v_add_f32_e32 v120, v121, v121
	v_add_f32_e32 v118, v116, v117
	v_pk_mul_f32 v[116:117], v[120:121], v[122:123] op_sel_hi:[1,0]
	v_add_u32_e32 v123, 0x80, v1
	v_mul_f32_e32 v120, v122, v116
	v_mul_f32_e32 v119, v119, v120
	v_sub_f32_e32 v118, v118, v119
	v_add_f32_e32 v119, v115, v193
	v_pk_fma_f32 v[116:117], v[184:185], v[116:117], v[118:119] neg_lo:[1,0,0] neg_hi:[1,0,0]
	v_pk_mul_f32 v[110:111], v[110:111], v[122:123] op_sel_hi:[1,0]
	v_pk_mul_f32 v[120:121], v[116:117], s[8:9] op_sel_hi:[1,0]
	v_pk_mul_f32 v[112:113], v[112:113], v[122:123] op_sel_hi:[1,0]
	v_fma_f32 v115, -v121, v121, v120
	v_add_f32_e32 v115, 0x3727c5ac, v115
	v_mul_f32_e32 v116, 0x4f800000, v115
	v_cmp_gt_f32_e32 vcc, s3, v115
	v_pk_fma_f32 v[112:113], v[40:41], v[112:113], v[48:49]
	v_pk_mul_f32 v[106:107], v[106:107], v[122:123] op_sel_hi:[1,0]
	v_cndmask_b32_e32 v115, v115, v116, vcc
	v_sqrt_f32_e32 v118, v115
	v_lshl_add_u64 v[116:117], s[84:85], 0, v[124:125]
	v_lshl_add_u64 v[126:127], v[116:117], 0, v[154:155]
	v_lshl_add_u64 v[116:117], s[66:67], 0, v[124:125]
	v_add_u32_e32 v119, -1, v118
	v_fma_f32 v120, -v119, v118, v115
	v_cmp_ge_f32_e64 s[6:7], 0, v120
	v_add_u32_e32 v120, 1, v118
	v_lshl_add_u64 v[124:125], v[116:117], 0, v[154:155]
	v_cndmask_b32_e64 v119, v118, v119, s[6:7]
	v_fma_f32 v118, -v120, v118, v115
	v_cmp_lt_f32_e64 s[6:7], 0, v118
	v_pk_fma_f32 v[106:107], v[26:27], v[106:107], v[42:43]
	v_pk_mul_f32 v[108:109], v[108:109], v[122:123] op_sel_hi:[1,0]
	v_cndmask_b32_e64 v118, v119, v120, s[6:7]
	v_mul_f32_e32 v119, 0x37800000, v118
	v_cndmask_b32_e32 v118, v118, v119, vcc
	v_cmp_class_f32_e32 vcc, v115, v198
	v_pk_fma_f32 v[108:109], v[28:29], v[108:109], v[44:45]
	v_fmac_f32_e32 v102, 0xba800000, v114
	v_cndmask_b32_e32 v115, v118, v115, vcc
	v_div_scale_f32 v118, s[0:1], v115, v115, 1.0
	v_rcp_f32_e32 v119, v118
	v_pk_mul_f32 v[102:103], v[102:103], v[122:123] op_sel_hi:[1,0]
	v_pk_mul_f32 v[104:105], v[104:105], v[122:123] op_sel_hi:[1,0]
	v_fmamk_f32 v101, v114, 0xba800000, v101
	v_fma_f32 v116, -v118, v119, 1.0
	v_fmac_f32_e32 v119, v116, v119
	v_div_scale_f32 v116, vcc, 1.0, v115, 1.0
	v_mul_f32_e32 v117, v116, v119
	v_fma_f32 v120, -v118, v117, v116
	v_fmac_f32_e32 v117, v120, v119
	v_fma_f32 v116, -v118, v117, v116
	v_div_fmas_f32 v116, v116, v119, v117
	v_div_fixup_f32 v120, v116, v115, 1.0
	v_pk_fma_f32 v[116:117], v[38:39], v[110:111], v[46:47]
	v_pk_fma_f32 v[104:105], v[32:33], v[104:105], v[36:37]
	v_cvt_pk_bf16_f32 v110, v116, v117
	v_cvt_pk_bf16_f32 v111, v112, v113
	v_sub_f32_e32 v113, v113, v121
	v_sub_f32_e32 v112, v112, v121
	v_sub_f32_e32 v117, v117, v121
	v_sub_f32_e32 v116, v116, v121
	v_pk_mul_f32 v[116:117], v[116:117], v[120:121] op_sel_hi:[1,0]
	v_pk_mul_f32 v[112:113], v[112:113], v[120:121] op_sel_hi:[1,0]
	v_pk_fma_f32 v[116:117], v[182:183], v[116:117], v[174:175]
	v_pk_fma_f32 v[112:113], v[160:161], v[112:113], v[176:177]
	v_cvt_pk_bf16_f32 v116, v116, v117
	v_fmamk_f32 v100, v114, 0xba800000, v100
	v_cvt_pk_bf16_f32 v117, v112, v113
	v_cvt_pk_bf16_f32 v112, v106, v107
	v_sub_f32_e32 v107, v107, v121
	v_sub_f32_e32 v106, v106, v121
	v_pk_mul_f32 v[106:107], v[106:107], v[120:121] op_sel_hi:[1,0]
	v_cvt_pk_bf16_f32 v113, v108, v109
	v_sub_f32_e32 v109, v109, v121
	v_sub_f32_e32 v108, v108, v121
	v_pk_fma_f32 v[106:107], v[158:159], v[106:107], v[170:171]
	v_pk_mul_f32 v[108:109], v[108:109], v[120:121] op_sel_hi:[1,0]
	v_cvt_pk_bf16_f32 v118, v106, v107
	v_pk_fma_f32 v[106:107], v[30:31], v[102:103], v[34:35]
	v_pk_fma_f32 v[108:109], v[156:157], v[108:109], v[172:173]
	v_fmamk_f32 v99, v114, 0xba800000, v99
	v_cvt_pk_bf16_f32 v119, v108, v109
	global_store_dwordx4 v[126:127], v[110:113], off
	global_store_dwordx4 v[124:125], v[116:119], off
	v_cvt_pk_bf16_f32 v102, v106, v107
	v_cvt_pk_bf16_f32 v103, v104, v105
	v_sub_f32_e32 v105, v105, v121
	v_sub_f32_e32 v104, v104, v121
	v_sub_f32_e32 v107, v107, v121
	v_sub_f32_e32 v106, v106, v121
	v_fmac_f32_e32 v98, 0xba800000, v114
	v_pk_mul_f32 v[106:107], v[106:107], v[120:121] op_sel_hi:[1,0]
	v_pk_mul_f32 v[104:105], v[104:105], v[120:121] op_sel_hi:[1,0]
	v_pk_mul_f32 v[98:99], v[98:99], v[122:123] op_sel_hi:[1,0]
	v_pk_mul_f32 v[100:101], v[100:101], v[122:123] op_sel_hi:[1,0]
	v_pk_fma_f32 v[104:105], v[150:151], v[104:105], v[168:169]
	v_pk_fma_f32 v[106:107], v[152:153], v[106:107], v[166:167]
	v_pk_fma_f32 v[100:101], v[20:21], v[100:101], v[24:25]
	v_pk_fma_f32 v[98:99], v[18:19], v[98:99], v[22:23]
	v_cvt_pk_bf16_f32 v106, v106, v107
	v_cvt_pk_bf16_f32 v107, v104, v105
	v_lshl_add_u32 v128, v123, 5, 0
	v_cvt_pk_bf16_f32 v104, v98, v99
	v_cvt_pk_bf16_f32 v105, v100, v101
	v_sub_f32_e32 v101, v101, v121
	v_sub_f32_e32 v100, v100, v121
	v_sub_f32_e32 v99, v99, v121
	v_sub_f32_e32 v98, v98, v121
	v_pk_mul_f32 v[98:99], v[98:99], v[120:121] op_sel_hi:[1,0]
	v_pk_mul_f32 v[100:101], v[100:101], v[120:121] op_sel_hi:[1,0]
	v_pk_fma_f32 v[98:99], v[148:149], v[98:99], v[162:163]
	v_pk_fma_f32 v[100:101], v[146:147], v[100:101], v[164:165]
	v_cvt_pk_bf16_f32 v108, v98, v99
	s_nop 0
	v_cvt_pk_bf16_f32 v109, v100, v101
	global_store_dwordx4 v[126:127], v[102:105], off offset:256
	global_store_dwordx4 v[124:125], v[106:109], off offset:256
	ds_read_b128 v[98:101], v128 offset:24576
	ds_read_b64 v[102:103], v128 offset:24592
	s_waitcnt lgkmcnt(1)
	v_mul_f32_e32 v105, 0x3a800000, v98
	v_mov_b32_e32 v104, v99
	v_mov_b32_e32 v189, v105
	v_pk_mul_f32 v[106:107], v[104:105], v[188:189]
	s_waitcnt lgkmcnt(0)
	v_mov_b32_e32 v186, v102
	v_sub_f32_e32 v99, v106, v107
	v_add_f32_e32 v99, 0x3727c5ac, v99
	v_mul_f32_e32 v104, 0x4f800000, v99
	v_cmp_gt_f32_e32 vcc, s3, v99
	v_fmamk_f32 v97, v98, 0xba800000, v97
	v_fmamk_f32 v96, v98, 0xba800000, v96
	v_cndmask_b32_e32 v99, v99, v104, vcc
	v_sqrt_f32_e32 v104, v99
	v_fmamk_f32 v95, v98, 0xba800000, v95
	v_fmac_f32_e32 v94, 0xba800000, v98
	v_fmamk_f32 v91, v98, 0xba800000, v91
	v_add_u32_e32 v106, -1, v104
	v_fma_f32 v108, -v106, v104, v99
	v_cmp_ge_f32_e64 s[6:7], 0, v108
	v_add_u32_e32 v108, 1, v104
	v_fmac_f32_e32 v90, 0xba800000, v98
	v_cndmask_b32_e64 v106, v104, v106, s[6:7]
	v_fma_f32 v104, -v108, v104, v99
	v_cmp_lt_f32_e64 s[6:7], 0, v104
	v_fmamk_f32 v93, v98, 0xba800000, v93
	v_fmamk_f32 v92, v98, 0xba800000, v92
	v_cndmask_b32_e64 v104, v106, v108, s[6:7]
	v_mul_f32_e32 v106, 0x37800000, v104
	v_cndmask_b32_e32 v104, v104, v106, vcc
	v_cmp_class_f32_e32 vcc, v99, v198
	v_add_u32_e32 v108, s26, v123
	v_ashrrev_i32_e32 v109, 31, v108
	v_cndmask_b32_e32 v99, v104, v99, vcc
	v_div_scale_f32 v104, s[0:1], v99, v99, 1.0
	v_rcp_f32_e32 v106, v104
	v_lshlrev_b64 v[108:109], 11, v[108:109]
	v_fmamk_f32 v89, v98, 0xba800000, v89
	v_fmamk_f32 v88, v98, 0xba800000, v88
	v_fma_f32 v110, -v104, v106, 1.0
	v_fmac_f32_e32 v106, v110, v106
	v_div_scale_f32 v110, vcc, 1.0, v99, 1.0
	v_mul_f32_e32 v111, v110, v106
	v_fma_f32 v112, -v104, v111, v110
	v_fmac_f32_e32 v111, v112, v106
	v_fma_f32 v104, -v104, v111, v110
	v_div_fmas_f32 v104, v104, v106, v111
	v_div_fixup_f32 v106, v104, v99, 1.0
	v_mul_f32_e32 v99, v100, v106
	v_mul_f32_e32 v100, v106, v106
	v_mul_f32_e32 v191, v107, v106
	v_fma_f32 v104, v101, v100, v192
	v_pk_mul_f32 v[100:101], v[106:107], v[190:191] op_sel_hi:[0,1]
	v_pk_mul_f32 v[100:101], v[186:187], v[100:101]
	v_fmamk_f32 v87, v98, 0xba800000, v87
	v_add_f32_e32 v101, v104, v101
	v_add_f32_e32 v104, v105, v105
	v_add_f32_e32 v102, v100, v101
	v_pk_mul_f32 v[100:101], v[104:105], v[106:107] op_sel_hi:[1,0]
	v_add_u32_e32 v107, 0x90, v1
	v_mul_f32_e32 v104, v106, v100
	v_mul_f32_e32 v103, v103, v104
	v_sub_f32_e32 v102, v102, v103
	v_add_f32_e32 v103, v99, v193
	v_pk_fma_f32 v[100:101], v[184:185], v[100:101], v[102:103] neg_lo:[1,0,0] neg_hi:[1,0,0]
	v_pk_mul_f32 v[94:95], v[94:95], v[106:107] op_sel_hi:[1,0]
	v_pk_mul_f32 v[104:105], v[100:101], s[8:9] op_sel_hi:[1,0]
	v_pk_mul_f32 v[96:97], v[96:97], v[106:107] op_sel_hi:[1,0]
	v_fma_f32 v99, -v105, v105, v104
	v_add_f32_e32 v99, 0x3727c5ac, v99
	v_mul_f32_e32 v100, 0x4f800000, v99
	v_cmp_gt_f32_e32 vcc, s3, v99
	v_pk_fma_f32 v[96:97], v[40:41], v[96:97], v[48:49]
	v_pk_mul_f32 v[90:91], v[90:91], v[106:107] op_sel_hi:[1,0]
	v_cndmask_b32_e32 v99, v99, v100, vcc
	v_sqrt_f32_e32 v102, v99
	v_lshl_add_u64 v[100:101], s[84:85], 0, v[108:109]
	v_lshl_add_u64 v[110:111], v[100:101], 0, v[154:155]
	v_lshl_add_u64 v[100:101], s[66:67], 0, v[108:109]
	v_add_u32_e32 v103, -1, v102
	v_fma_f32 v104, -v103, v102, v99
	v_cmp_ge_f32_e64 s[6:7], 0, v104
	v_add_u32_e32 v104, 1, v102
	v_lshl_add_u64 v[108:109], v[100:101], 0, v[154:155]
	v_cndmask_b32_e64 v103, v102, v103, s[6:7]
	v_fma_f32 v102, -v104, v102, v99
	v_cmp_lt_f32_e64 s[6:7], 0, v102
	v_pk_fma_f32 v[90:91], v[26:27], v[90:91], v[42:43]
	v_pk_mul_f32 v[92:93], v[92:93], v[106:107] op_sel_hi:[1,0]
	v_cndmask_b32_e64 v102, v103, v104, s[6:7]
	v_mul_f32_e32 v103, 0x37800000, v102
	v_cndmask_b32_e32 v102, v102, v103, vcc
	v_cmp_class_f32_e32 vcc, v99, v198
	v_pk_fma_f32 v[92:93], v[28:29], v[92:93], v[44:45]
	v_fmac_f32_e32 v86, 0xba800000, v98
	v_cndmask_b32_e32 v99, v102, v99, vcc
	v_div_scale_f32 v102, s[0:1], v99, v99, 1.0
	v_rcp_f32_e32 v103, v102
	v_pk_mul_f32 v[86:87], v[86:87], v[106:107] op_sel_hi:[1,0]
	v_pk_mul_f32 v[88:89], v[88:89], v[106:107] op_sel_hi:[1,0]
	v_fmamk_f32 v85, v98, 0xba800000, v85
	v_fma_f32 v100, -v102, v103, 1.0
	v_fmac_f32_e32 v103, v100, v103
	v_div_scale_f32 v100, vcc, 1.0, v99, 1.0
	v_mul_f32_e32 v101, v100, v103
	v_fma_f32 v104, -v102, v101, v100
	v_fmac_f32_e32 v101, v104, v103
	v_fma_f32 v100, -v102, v101, v100
	v_div_fmas_f32 v100, v100, v103, v101
	v_div_fixup_f32 v104, v100, v99, 1.0
	v_pk_fma_f32 v[100:101], v[38:39], v[94:95], v[46:47]
	v_pk_fma_f32 v[88:89], v[32:33], v[88:89], v[36:37]
	v_cvt_pk_bf16_f32 v94, v100, v101
	v_cvt_pk_bf16_f32 v95, v96, v97
	v_sub_f32_e32 v97, v97, v105
	v_sub_f32_e32 v96, v96, v105
	v_sub_f32_e32 v101, v101, v105
	v_sub_f32_e32 v100, v100, v105
	v_pk_mul_f32 v[100:101], v[100:101], v[104:105] op_sel_hi:[1,0]
	v_pk_mul_f32 v[96:97], v[96:97], v[104:105] op_sel_hi:[1,0]
	v_pk_fma_f32 v[100:101], v[182:183], v[100:101], v[174:175]
	v_pk_fma_f32 v[96:97], v[160:161], v[96:97], v[176:177]
	v_cvt_pk_bf16_f32 v100, v100, v101
	v_fmamk_f32 v84, v98, 0xba800000, v84
	v_cvt_pk_bf16_f32 v101, v96, v97
	v_cvt_pk_bf16_f32 v96, v90, v91
	v_sub_f32_e32 v91, v91, v105
	v_sub_f32_e32 v90, v90, v105
	v_pk_mul_f32 v[90:91], v[90:91], v[104:105] op_sel_hi:[1,0]
	v_cvt_pk_bf16_f32 v97, v92, v93
	v_sub_f32_e32 v93, v93, v105
	v_sub_f32_e32 v92, v92, v105
	v_pk_fma_f32 v[90:91], v[158:159], v[90:91], v[170:171]
	v_pk_mul_f32 v[92:93], v[92:93], v[104:105] op_sel_hi:[1,0]
	v_cvt_pk_bf16_f32 v102, v90, v91
	v_pk_fma_f32 v[90:91], v[30:31], v[86:87], v[34:35]
	v_pk_fma_f32 v[92:93], v[156:157], v[92:93], v[172:173]
	v_fmamk_f32 v83, v98, 0xba800000, v83
	v_cvt_pk_bf16_f32 v103, v92, v93
	global_store_dwordx4 v[110:111], v[94:97], off
	global_store_dwordx4 v[108:109], v[100:103], off
	v_cvt_pk_bf16_f32 v86, v90, v91
	v_cvt_pk_bf16_f32 v87, v88, v89
	v_sub_f32_e32 v89, v89, v105
	v_sub_f32_e32 v88, v88, v105
	v_sub_f32_e32 v91, v91, v105
	v_sub_f32_e32 v90, v90, v105
	v_fmac_f32_e32 v82, 0xba800000, v98
	v_pk_mul_f32 v[90:91], v[90:91], v[104:105] op_sel_hi:[1,0]
	v_pk_mul_f32 v[88:89], v[88:89], v[104:105] op_sel_hi:[1,0]
	v_pk_mul_f32 v[82:83], v[82:83], v[106:107] op_sel_hi:[1,0]
	v_pk_mul_f32 v[84:85], v[84:85], v[106:107] op_sel_hi:[1,0]
	v_pk_fma_f32 v[88:89], v[150:151], v[88:89], v[168:169]
	v_pk_fma_f32 v[90:91], v[152:153], v[90:91], v[166:167]
	v_pk_fma_f32 v[84:85], v[20:21], v[84:85], v[24:25]
	v_pk_fma_f32 v[82:83], v[18:19], v[82:83], v[22:23]
	v_cvt_pk_bf16_f32 v90, v90, v91
	v_cvt_pk_bf16_f32 v91, v88, v89
	v_lshl_add_u32 v112, v107, 5, 0
	v_cvt_pk_bf16_f32 v88, v82, v83
	v_cvt_pk_bf16_f32 v89, v84, v85
	v_sub_f32_e32 v85, v85, v105
	v_sub_f32_e32 v84, v84, v105
	v_sub_f32_e32 v83, v83, v105
	v_sub_f32_e32 v82, v82, v105
	v_pk_mul_f32 v[82:83], v[82:83], v[104:105] op_sel_hi:[1,0]
	v_pk_mul_f32 v[84:85], v[84:85], v[104:105] op_sel_hi:[1,0]
	v_pk_fma_f32 v[82:83], v[148:149], v[82:83], v[162:163]
	v_pk_fma_f32 v[84:85], v[146:147], v[84:85], v[164:165]
	v_cvt_pk_bf16_f32 v92, v82, v83
	s_nop 0
	v_cvt_pk_bf16_f32 v93, v84, v85
	global_store_dwordx4 v[110:111], v[86:89], off offset:256
	global_store_dwordx4 v[108:109], v[90:93], off offset:256
	ds_read_b128 v[82:85], v112 offset:24576
	ds_read_b64 v[86:87], v112 offset:24592
	s_waitcnt lgkmcnt(1)
	v_mul_f32_e32 v89, 0x3a800000, v82
	v_mov_b32_e32 v88, v83
	v_mov_b32_e32 v189, v89
	v_pk_mul_f32 v[90:91], v[88:89], v[188:189]
	s_waitcnt lgkmcnt(0)
	v_mov_b32_e32 v186, v86
	v_sub_f32_e32 v83, v90, v91
	v_add_f32_e32 v83, 0x3727c5ac, v83
	v_mul_f32_e32 v88, 0x4f800000, v83
	v_cmp_gt_f32_e32 vcc, s3, v83
	v_fmamk_f32 v81, v82, 0xba800000, v81
	v_fmamk_f32 v80, v82, 0xba800000, v80
	v_cndmask_b32_e32 v83, v83, v88, vcc
	v_sqrt_f32_e32 v88, v83
	v_fmamk_f32 v79, v82, 0xba800000, v79
	v_fmac_f32_e32 v78, 0xba800000, v82
	v_fmamk_f32 v75, v82, 0xba800000, v75
	v_add_u32_e32 v90, -1, v88
	v_fma_f32 v92, -v90, v88, v83
	v_cmp_ge_f32_e64 s[6:7], 0, v92
	v_add_u32_e32 v92, 1, v88
	v_fmac_f32_e32 v74, 0xba800000, v82
	v_cndmask_b32_e64 v90, v88, v90, s[6:7]
	v_fma_f32 v88, -v92, v88, v83
	v_cmp_lt_f32_e64 s[6:7], 0, v88
	v_fmamk_f32 v77, v82, 0xba800000, v77
	v_fmamk_f32 v76, v82, 0xba800000, v76
	v_cndmask_b32_e64 v88, v90, v92, s[6:7]
	v_mul_f32_e32 v90, 0x37800000, v88
	v_cndmask_b32_e32 v88, v88, v90, vcc
	v_cmp_class_f32_e32 vcc, v83, v198
	v_add_u32_e32 v92, s26, v107
	v_ashrrev_i32_e32 v93, 31, v92
	v_cndmask_b32_e32 v83, v88, v83, vcc
	v_div_scale_f32 v88, s[0:1], v83, v83, 1.0
	v_rcp_f32_e32 v90, v88
	v_lshlrev_b64 v[92:93], 11, v[92:93]
	v_fmamk_f32 v73, v82, 0xba800000, v73
	v_fmamk_f32 v72, v82, 0xba800000, v72
	v_fma_f32 v94, -v88, v90, 1.0
	v_fmac_f32_e32 v90, v94, v90
	v_div_scale_f32 v94, vcc, 1.0, v83, 1.0
	v_mul_f32_e32 v95, v94, v90
	v_fma_f32 v96, -v88, v95, v94
	v_fmac_f32_e32 v95, v96, v90
	v_fma_f32 v88, -v88, v95, v94
	v_div_fmas_f32 v88, v88, v90, v95
	v_div_fixup_f32 v90, v88, v83, 1.0
	v_mul_f32_e32 v83, v84, v90
	v_mul_f32_e32 v84, v90, v90
	v_mul_f32_e32 v191, v91, v90
	v_fma_f32 v88, v85, v84, v192
	v_pk_mul_f32 v[84:85], v[90:91], v[190:191] op_sel_hi:[0,1]
	v_pk_mul_f32 v[84:85], v[186:187], v[84:85]
	v_fmamk_f32 v71, v82, 0xba800000, v71
	v_add_f32_e32 v85, v88, v85
	v_add_f32_e32 v88, v89, v89
	v_add_f32_e32 v86, v84, v85
	v_pk_mul_f32 v[84:85], v[88:89], v[90:91] op_sel_hi:[1,0]
	v_add_u32_e32 v91, 0xa0, v1
	v_mul_f32_e32 v88, v90, v84
	v_mul_f32_e32 v87, v87, v88
	v_sub_f32_e32 v86, v86, v87
	v_add_f32_e32 v87, v83, v193
	v_pk_fma_f32 v[84:85], v[184:185], v[84:85], v[86:87] neg_lo:[1,0,0] neg_hi:[1,0,0]
	v_pk_mul_f32 v[78:79], v[78:79], v[90:91] op_sel_hi:[1,0]
	v_pk_mul_f32 v[88:89], v[84:85], s[8:9] op_sel_hi:[1,0]
	v_pk_mul_f32 v[80:81], v[80:81], v[90:91] op_sel_hi:[1,0]
	v_fma_f32 v83, -v89, v89, v88
	v_add_f32_e32 v83, 0x3727c5ac, v83
	v_mul_f32_e32 v84, 0x4f800000, v83
	v_cmp_gt_f32_e32 vcc, s3, v83
	v_pk_fma_f32 v[80:81], v[40:41], v[80:81], v[48:49]
	v_pk_mul_f32 v[74:75], v[74:75], v[90:91] op_sel_hi:[1,0]
	v_cndmask_b32_e32 v83, v83, v84, vcc
	v_sqrt_f32_e32 v86, v83
	v_lshl_add_u64 v[84:85], s[84:85], 0, v[92:93]
	v_lshl_add_u64 v[94:95], v[84:85], 0, v[154:155]
	v_lshl_add_u64 v[84:85], s[66:67], 0, v[92:93]
	v_add_u32_e32 v87, -1, v86
	v_fma_f32 v88, -v87, v86, v83
	v_cmp_ge_f32_e64 s[6:7], 0, v88
	v_add_u32_e32 v88, 1, v86
	v_lshl_add_u64 v[92:93], v[84:85], 0, v[154:155]
	v_cndmask_b32_e64 v87, v86, v87, s[6:7]
	v_fma_f32 v86, -v88, v86, v83
	v_cmp_lt_f32_e64 s[6:7], 0, v86
	v_pk_fma_f32 v[74:75], v[26:27], v[74:75], v[42:43]
	v_pk_mul_f32 v[76:77], v[76:77], v[90:91] op_sel_hi:[1,0]
	v_cndmask_b32_e64 v86, v87, v88, s[6:7]
	v_mul_f32_e32 v87, 0x37800000, v86
	v_cndmask_b32_e32 v86, v86, v87, vcc
	v_cmp_class_f32_e32 vcc, v83, v198
	v_pk_fma_f32 v[76:77], v[28:29], v[76:77], v[44:45]
	v_fmac_f32_e32 v70, 0xba800000, v82
	v_cndmask_b32_e32 v83, v86, v83, vcc
	v_div_scale_f32 v86, s[0:1], v83, v83, 1.0
	v_rcp_f32_e32 v87, v86
	v_pk_mul_f32 v[70:71], v[70:71], v[90:91] op_sel_hi:[1,0]
	v_pk_mul_f32 v[72:73], v[72:73], v[90:91] op_sel_hi:[1,0]
	v_fmamk_f32 v69, v82, 0xba800000, v69
	v_fma_f32 v84, -v86, v87, 1.0
	v_fmac_f32_e32 v87, v84, v87
	v_div_scale_f32 v84, vcc, 1.0, v83, 1.0
	v_mul_f32_e32 v85, v84, v87
	v_fma_f32 v88, -v86, v85, v84
	v_fmac_f32_e32 v85, v88, v87
	v_fma_f32 v84, -v86, v85, v84
	v_div_fmas_f32 v84, v84, v87, v85
	v_div_fixup_f32 v88, v84, v83, 1.0
	v_pk_fma_f32 v[84:85], v[38:39], v[78:79], v[46:47]
	v_pk_fma_f32 v[72:73], v[32:33], v[72:73], v[36:37]
	v_cvt_pk_bf16_f32 v78, v84, v85
	v_cvt_pk_bf16_f32 v79, v80, v81
	v_sub_f32_e32 v81, v81, v89
	v_sub_f32_e32 v80, v80, v89
	v_sub_f32_e32 v85, v85, v89
	v_sub_f32_e32 v84, v84, v89
	v_pk_mul_f32 v[84:85], v[84:85], v[88:89] op_sel_hi:[1,0]
	v_pk_mul_f32 v[80:81], v[80:81], v[88:89] op_sel_hi:[1,0]
	v_pk_fma_f32 v[84:85], v[182:183], v[84:85], v[174:175]
	v_pk_fma_f32 v[80:81], v[160:161], v[80:81], v[176:177]
	v_cvt_pk_bf16_f32 v84, v84, v85
	v_fmamk_f32 v68, v82, 0xba800000, v68
	v_cvt_pk_bf16_f32 v85, v80, v81
	v_cvt_pk_bf16_f32 v80, v74, v75
	v_sub_f32_e32 v75, v75, v89
	v_sub_f32_e32 v74, v74, v89
	v_pk_mul_f32 v[74:75], v[74:75], v[88:89] op_sel_hi:[1,0]
	v_cvt_pk_bf16_f32 v81, v76, v77
	v_sub_f32_e32 v77, v77, v89
	v_sub_f32_e32 v76, v76, v89
	v_pk_fma_f32 v[74:75], v[158:159], v[74:75], v[170:171]
	v_pk_mul_f32 v[76:77], v[76:77], v[88:89] op_sel_hi:[1,0]
	v_cvt_pk_bf16_f32 v86, v74, v75
	v_pk_fma_f32 v[74:75], v[30:31], v[70:71], v[34:35]
	v_pk_fma_f32 v[76:77], v[156:157], v[76:77], v[172:173]
	v_fmamk_f32 v67, v82, 0xba800000, v67
	v_cvt_pk_bf16_f32 v87, v76, v77
	global_store_dwordx4 v[94:95], v[78:81], off
	global_store_dwordx4 v[92:93], v[84:87], off
	v_cvt_pk_bf16_f32 v70, v74, v75
	v_cvt_pk_bf16_f32 v71, v72, v73
	v_sub_f32_e32 v73, v73, v89
	v_sub_f32_e32 v72, v72, v89
	v_sub_f32_e32 v75, v75, v89
	v_sub_f32_e32 v74, v74, v89
	v_fmac_f32_e32 v66, 0xba800000, v82
	v_pk_mul_f32 v[74:75], v[74:75], v[88:89] op_sel_hi:[1,0]
	v_pk_mul_f32 v[72:73], v[72:73], v[88:89] op_sel_hi:[1,0]
	v_pk_mul_f32 v[66:67], v[66:67], v[90:91] op_sel_hi:[1,0]
	v_pk_mul_f32 v[68:69], v[68:69], v[90:91] op_sel_hi:[1,0]
	v_pk_fma_f32 v[72:73], v[150:151], v[72:73], v[168:169]
	v_pk_fma_f32 v[74:75], v[152:153], v[74:75], v[166:167]
	v_pk_fma_f32 v[68:69], v[20:21], v[68:69], v[24:25]
	v_pk_fma_f32 v[66:67], v[18:19], v[66:67], v[22:23]
	v_cvt_pk_bf16_f32 v74, v74, v75
	v_cvt_pk_bf16_f32 v75, v72, v73
	v_lshl_add_u32 v96, v91, 5, 0
	v_cvt_pk_bf16_f32 v72, v66, v67
	v_cvt_pk_bf16_f32 v73, v68, v69
	v_sub_f32_e32 v69, v69, v89
	v_sub_f32_e32 v68, v68, v89
	v_sub_f32_e32 v67, v67, v89
	v_sub_f32_e32 v66, v66, v89
	v_pk_mul_f32 v[66:67], v[66:67], v[88:89] op_sel_hi:[1,0]
	v_pk_mul_f32 v[68:69], v[68:69], v[88:89] op_sel_hi:[1,0]
	v_pk_fma_f32 v[66:67], v[148:149], v[66:67], v[162:163]
	v_pk_fma_f32 v[68:69], v[146:147], v[68:69], v[164:165]
	v_cvt_pk_bf16_f32 v76, v66, v67
	v_add_u32_e32 v1, 0xb0, v1
	v_cvt_pk_bf16_f32 v77, v68, v69
	global_store_dwordx4 v[94:95], v[70:73], off offset:256
	global_store_dwordx4 v[92:93], v[74:77], off offset:256
	ds_read_b128 v[66:69], v96 offset:24576
	ds_read_b64 v[70:71], v96 offset:24592
	s_waitcnt lgkmcnt(1)
	v_mul_f32_e32 v73, 0x3a800000, v66
	v_mov_b32_e32 v72, v67
	v_mov_b32_e32 v189, v73
	v_pk_mul_f32 v[74:75], v[72:73], v[188:189]
	s_waitcnt lgkmcnt(0)
	v_mov_b32_e32 v186, v70
	v_sub_f32_e32 v67, v74, v75
	v_add_f32_e32 v67, 0x3727c5ac, v67
	v_mul_f32_e32 v72, 0x4f800000, v67
	v_cmp_gt_f32_e32 vcc, s3, v67
	v_fmamk_f32 v65, v66, 0xba800000, v65
	v_fmamk_f32 v64, v66, 0xba800000, v64
	v_cndmask_b32_e32 v67, v67, v72, vcc
	v_sqrt_f32_e32 v72, v67
	v_fmamk_f32 v63, v66, 0xba800000, v63
	v_fmac_f32_e32 v62, 0xba800000, v66
	v_fmamk_f32 v59, v66, 0xba800000, v59
	v_add_u32_e32 v74, -1, v72
	v_fma_f32 v76, -v74, v72, v67
	v_cmp_ge_f32_e64 s[6:7], 0, v76
	v_add_u32_e32 v76, 1, v72
	v_fmac_f32_e32 v58, 0xba800000, v66
	v_cndmask_b32_e64 v74, v72, v74, s[6:7]
	v_fma_f32 v72, -v76, v72, v67
	v_cmp_lt_f32_e64 s[6:7], 0, v72
	v_fmamk_f32 v61, v66, 0xba800000, v61
	v_fmamk_f32 v60, v66, 0xba800000, v60
	v_cndmask_b32_e64 v72, v74, v76, s[6:7]
	v_mul_f32_e32 v74, 0x37800000, v72
	v_cndmask_b32_e32 v72, v72, v74, vcc
	v_cmp_class_f32_e32 vcc, v67, v198
	v_add_u32_e32 v76, s26, v91
	v_ashrrev_i32_e32 v77, 31, v76
	v_cndmask_b32_e32 v67, v72, v67, vcc
	v_div_scale_f32 v72, s[0:1], v67, v67, 1.0
	v_rcp_f32_e32 v74, v72
	v_lshlrev_b64 v[76:77], 11, v[76:77]
	v_fmamk_f32 v57, v66, 0xba800000, v57
	v_fmamk_f32 v56, v66, 0xba800000, v56
	v_fma_f32 v78, -v72, v74, 1.0
	v_fmac_f32_e32 v74, v78, v74
	v_div_scale_f32 v78, vcc, 1.0, v67, 1.0
	v_mul_f32_e32 v79, v78, v74
	v_fma_f32 v80, -v72, v79, v78
	v_fmac_f32_e32 v79, v80, v74
	v_fma_f32 v72, -v72, v79, v78
	v_div_fmas_f32 v72, v72, v74, v79
	v_div_fixup_f32 v74, v72, v67, 1.0
	v_mul_f32_e32 v67, v68, v74
	v_mul_f32_e32 v68, v74, v74
	v_mul_f32_e32 v191, v75, v74
	v_fma_f32 v72, v69, v68, v192
	v_pk_mul_f32 v[68:69], v[74:75], v[190:191] op_sel_hi:[0,1]
	v_pk_mul_f32 v[68:69], v[186:187], v[68:69]
	v_fmamk_f32 v55, v66, 0xba800000, v55
	v_add_f32_e32 v69, v72, v69
	v_add_f32_e32 v72, v73, v73
	v_add_f32_e32 v70, v68, v69
	v_pk_mul_f32 v[68:69], v[72:73], v[74:75] op_sel_hi:[1,0]
	v_lshl_add_u32 v75, v1, 5, 0
	v_mul_f32_e32 v72, v74, v68
	v_mul_f32_e32 v71, v71, v72
	v_sub_f32_e32 v70, v70, v71
	v_add_f32_e32 v71, v67, v193
	v_pk_fma_f32 v[68:69], v[184:185], v[68:69], v[70:71] neg_lo:[1,0,0] neg_hi:[1,0,0]
	v_pk_mul_f32 v[62:63], v[62:63], v[74:75] op_sel_hi:[1,0]
	v_pk_mul_f32 v[72:73], v[68:69], s[8:9] op_sel_hi:[1,0]
	v_pk_mul_f32 v[64:65], v[64:65], v[74:75] op_sel_hi:[1,0]
	v_fma_f32 v67, -v73, v73, v72
	v_add_f32_e32 v67, 0x3727c5ac, v67
	v_mul_f32_e32 v68, 0x4f800000, v67
	v_cmp_gt_f32_e32 vcc, s3, v67
	v_pk_fma_f32 v[64:65], v[40:41], v[64:65], v[48:49]
	v_pk_mul_f32 v[58:59], v[58:59], v[74:75] op_sel_hi:[1,0]
	v_cndmask_b32_e32 v67, v67, v68, vcc
	v_sqrt_f32_e32 v70, v67
	v_lshl_add_u64 v[68:69], s[84:85], 0, v[76:77]
	v_lshl_add_u64 v[78:79], v[68:69], 0, v[154:155]
	v_lshl_add_u64 v[68:69], s[66:67], 0, v[76:77]
	v_add_u32_e32 v71, -1, v70
	v_fma_f32 v72, -v71, v70, v67
	v_cmp_ge_f32_e64 s[6:7], 0, v72
	v_add_u32_e32 v72, 1, v70
	v_lshl_add_u64 v[76:77], v[68:69], 0, v[154:155]
	v_cndmask_b32_e64 v71, v70, v71, s[6:7]
	v_fma_f32 v70, -v72, v70, v67
	v_cmp_lt_f32_e64 s[6:7], 0, v70
	v_pk_fma_f32 v[58:59], v[26:27], v[58:59], v[42:43]
	v_pk_mul_f32 v[60:61], v[60:61], v[74:75] op_sel_hi:[1,0]
	v_cndmask_b32_e64 v70, v71, v72, s[6:7]
	v_mul_f32_e32 v71, 0x37800000, v70
	v_cndmask_b32_e32 v70, v70, v71, vcc
	v_cmp_class_f32_e32 vcc, v67, v198
	v_pk_fma_f32 v[60:61], v[28:29], v[60:61], v[44:45]
	v_fmac_f32_e32 v54, 0xba800000, v66
	v_cndmask_b32_e32 v67, v70, v67, vcc
	v_div_scale_f32 v70, s[0:1], v67, v67, 1.0
	v_rcp_f32_e32 v71, v70
	v_pk_mul_f32 v[54:55], v[54:55], v[74:75] op_sel_hi:[1,0]
	v_pk_mul_f32 v[56:57], v[56:57], v[74:75] op_sel_hi:[1,0]
	v_fmamk_f32 v53, v66, 0xba800000, v53
	v_fma_f32 v68, -v70, v71, 1.0
	v_fmac_f32_e32 v71, v68, v71
	v_div_scale_f32 v68, vcc, 1.0, v67, 1.0
	v_mul_f32_e32 v69, v68, v71
	v_fma_f32 v72, -v70, v69, v68
	v_fmac_f32_e32 v69, v72, v71
	v_fma_f32 v68, -v70, v69, v68
	v_div_fmas_f32 v68, v68, v71, v69
	v_div_fixup_f32 v72, v68, v67, 1.0
	v_pk_fma_f32 v[68:69], v[38:39], v[62:63], v[46:47]
	v_pk_fma_f32 v[56:57], v[32:33], v[56:57], v[36:37]
	v_cvt_pk_bf16_f32 v62, v68, v69
	v_cvt_pk_bf16_f32 v63, v64, v65
	v_sub_f32_e32 v65, v65, v73
	v_sub_f32_e32 v64, v64, v73
	v_sub_f32_e32 v69, v69, v73
	v_sub_f32_e32 v68, v68, v73
	v_pk_mul_f32 v[68:69], v[68:69], v[72:73] op_sel_hi:[1,0]
	v_pk_mul_f32 v[64:65], v[64:65], v[72:73] op_sel_hi:[1,0]
	v_pk_fma_f32 v[68:69], v[182:183], v[68:69], v[174:175]
	v_pk_fma_f32 v[64:65], v[160:161], v[64:65], v[176:177]
	v_cvt_pk_bf16_f32 v68, v68, v69
	v_fmamk_f32 v52, v66, 0xba800000, v52
	v_cvt_pk_bf16_f32 v69, v64, v65
	v_cvt_pk_bf16_f32 v64, v58, v59
	v_sub_f32_e32 v59, v59, v73
	v_sub_f32_e32 v58, v58, v73
	v_pk_mul_f32 v[58:59], v[58:59], v[72:73] op_sel_hi:[1,0]
	v_cvt_pk_bf16_f32 v65, v60, v61
	v_sub_f32_e32 v61, v61, v73
	v_sub_f32_e32 v60, v60, v73
	v_pk_fma_f32 v[58:59], v[158:159], v[58:59], v[170:171]
	v_pk_mul_f32 v[60:61], v[60:61], v[72:73] op_sel_hi:[1,0]
	v_cvt_pk_bf16_f32 v70, v58, v59
	v_pk_fma_f32 v[58:59], v[30:31], v[54:55], v[34:35]
	v_pk_fma_f32 v[60:61], v[156:157], v[60:61], v[172:173]
	v_fmamk_f32 v51, v66, 0xba800000, v51
	v_cvt_pk_bf16_f32 v71, v60, v61
	global_store_dwordx4 v[78:79], v[62:65], off
	global_store_dwordx4 v[76:77], v[68:71], off
	v_cvt_pk_bf16_f32 v54, v58, v59
	v_cvt_pk_bf16_f32 v55, v56, v57
	v_sub_f32_e32 v57, v57, v73
	v_sub_f32_e32 v56, v56, v73
	v_sub_f32_e32 v59, v59, v73
	v_sub_f32_e32 v58, v58, v73
	v_fmac_f32_e32 v50, 0xba800000, v66
	v_pk_mul_f32 v[58:59], v[58:59], v[72:73] op_sel_hi:[1,0]
	v_pk_mul_f32 v[56:57], v[56:57], v[72:73] op_sel_hi:[1,0]
	v_pk_mul_f32 v[50:51], v[50:51], v[74:75] op_sel_hi:[1,0]
	v_pk_mul_f32 v[52:53], v[52:53], v[74:75] op_sel_hi:[1,0]
	v_pk_fma_f32 v[56:57], v[150:151], v[56:57], v[168:169]
	v_pk_fma_f32 v[58:59], v[152:153], v[58:59], v[166:167]
	v_pk_fma_f32 v[52:53], v[20:21], v[52:53], v[24:25]
	v_pk_fma_f32 v[50:51], v[18:19], v[50:51], v[22:23]
	v_cvt_pk_bf16_f32 v58, v58, v59
	v_cvt_pk_bf16_f32 v59, v56, v57
	s_nop 0
	v_cvt_pk_bf16_f32 v56, v50, v51
	v_cvt_pk_bf16_f32 v57, v52, v53
	v_sub_f32_e32 v53, v53, v73
	v_sub_f32_e32 v52, v52, v73
	v_sub_f32_e32 v51, v51, v73
	v_sub_f32_e32 v50, v50, v73
	v_pk_mul_f32 v[50:51], v[50:51], v[72:73] op_sel_hi:[1,0]
	v_pk_mul_f32 v[52:53], v[52:53], v[72:73] op_sel_hi:[1,0]
	v_pk_fma_f32 v[50:51], v[148:149], v[50:51], v[162:163]
	v_pk_fma_f32 v[52:53], v[146:147], v[52:53], v[164:165]
	v_cvt_pk_bf16_f32 v60, v50, v51
	s_nop 0
	v_cvt_pk_bf16_f32 v61, v52, v53
	global_store_dwordx4 v[78:79], v[54:57], off offset:256
	global_store_dwordx4 v[76:77], v[58:61], off offset:256
	ds_read_b128 v[50:53], v75 offset:24576
	ds_read_b64 v[54:55], v75 offset:24592
	s_waitcnt lgkmcnt(1)
	v_mul_f32_e32 v57, 0x3a800000, v50
	v_mov_b32_e32 v56, v51
	v_mov_b32_e32 v189, v57
	v_pk_mul_f32 v[58:59], v[56:57], v[188:189]
	s_waitcnt lgkmcnt(0)
	v_mov_b32_e32 v186, v54
	v_sub_f32_e32 v56, v58, v59
	v_add_f32_e32 v56, 0x3727c5ac, v56
	v_mul_f32_e32 v58, 0x4f800000, v56
	v_cmp_gt_f32_e32 vcc, s3, v56
	v_fmamk_f32 v17, v50, 0xba800000, v17
	v_fmamk_f32 v16, v50, 0xba800000, v16
	v_cndmask_b32_e32 v56, v56, v58, vcc
	v_sqrt_f32_e32 v58, v56
	v_fmamk_f32 v15, v50, 0xba800000, v15
	v_fmac_f32_e32 v14, 0xba800000, v50
	v_fmamk_f32 v11, v50, 0xba800000, v11
	v_add_u32_e32 v60, -1, v58
	v_fma_f32 v61, -v60, v58, v56
	v_cmp_ge_f32_e64 s[6:7], 0, v61
	v_add_u32_e32 v61, 1, v58
	v_fmac_f32_e32 v10, 0xba800000, v50
	v_cndmask_b32_e64 v60, v58, v60, s[6:7]
	v_fma_f32 v58, -v61, v58, v56
	v_cmp_lt_f32_e64 s[6:7], 0, v58
	v_fmamk_f32 v13, v50, 0xba800000, v13
	v_fmamk_f32 v12, v50, 0xba800000, v12
	v_cndmask_b32_e64 v58, v60, v61, s[6:7]
	v_mul_f32_e32 v60, 0x37800000, v58
	v_cndmask_b32_e32 v58, v58, v60, vcc
	v_cmp_class_f32_e32 vcc, v56, v198
	v_mov_b32_e32 v60, v51
	v_mov_b32_e32 v61, v52
	v_cndmask_b32_e32 v56, v58, v56, vcc
	v_div_scale_f32 v58, s[0:1], v56, v56, 1.0
	v_rcp_f32_e32 v62, v58
	v_fmamk_f32 v9, v50, 0xba800000, v9
	v_fmamk_f32 v8, v50, 0xba800000, v8
	v_fmamk_f32 v7, v50, 0xba800000, v7
	v_fma_f32 v51, -v58, v62, 1.0
	v_fmac_f32_e32 v62, v51, v62
	v_div_scale_f32 v51, vcc, 1.0, v56, 1.0
	v_mul_f32_e32 v63, v51, v62
	v_fma_f32 v64, -v58, v63, v51
	v_fmac_f32_e32 v63, v64, v62
	v_fma_f32 v51, -v58, v63, v51
	v_div_fmas_f32 v51, v51, v62, v63
	v_div_fixup_f32 v58, v51, v56, 1.0
	v_mul_f32_e32 v191, v59, v58
	v_mul_f32_e32 v51, v58, v58
	v_pk_mul_f32 v[62:63], v[58:59], v[190:191] op_sel_hi:[0,1]
	v_fmac_f32_e32 v192, v53, v51
	v_pk_mul_f32 v[62:63], v[186:187], v[62:63]
	v_add_f32_e32 v56, v57, v57
	v_add_f32_e32 v51, v192, v63
	v_pk_mul_f32 v[56:57], v[56:57], v[58:59] op_sel_hi:[1,0]
	v_add_f32_e32 v192, v62, v51
	v_mul_f32_e32 v54, v58, v56
	v_mov_b32_e32 v62, v55
	v_mov_b32_e32 v63, v52
	v_mov_b32_e32 v55, v58
	v_pk_fma_f32 v[52:53], v[62:63], v[54:55], v[192:193] neg_lo:[1,0,0] neg_hi:[1,0,0]
	v_pk_fma_f32 v[54:55], v[60:61], v[58:59], v[192:193] op_sel_hi:[1,0,1]
	v_pk_mul_f32 v[14:15], v[14:15], v[58:59] op_sel_hi:[1,0]
	v_mov_b32_e32 v53, v55
	v_pk_fma_f32 v[52:53], v[184:185], v[56:57], v[52:53] neg_lo:[1,0,0] neg_hi:[1,0,0]
	v_pk_mul_f32 v[16:17], v[16:17], v[58:59] op_sel_hi:[1,0]
	v_pk_mul_f32 v[52:53], v[52:53], s[8:9] op_sel_hi:[1,0]
	v_pk_fma_f32 v[16:17], v[40:41], v[16:17], v[48:49]
	v_fma_f32 v51, -v53, v53, v52
	v_add_f32_e32 v51, 0x3727c5ac, v51
	v_mul_f32_e32 v52, 0x4f800000, v51
	v_cmp_gt_f32_e32 vcc, s3, v51
	v_pk_fma_f32 v[38:39], v[38:39], v[14:15], v[46:47]
	v_pk_mul_f32 v[10:11], v[10:11], v[58:59] op_sel_hi:[1,0]
	v_cndmask_b32_e32 v51, v51, v52, vcc
	v_sqrt_f32_e32 v52, v51
	v_cvt_pk_bf16_f32 v14, v38, v39
	v_cvt_pk_bf16_f32 v15, v16, v17
	v_sub_f32_e32 v17, v17, v53
	v_add_u32_e32 v54, -1, v52
	v_fma_f32 v55, -v54, v52, v51
	v_cmp_ge_f32_e64 s[6:7], 0, v55
	v_add_u32_e32 v55, 1, v52
	v_sub_f32_e32 v16, v16, v53
	v_cndmask_b32_e64 v54, v52, v54, s[6:7]
	v_fma_f32 v52, -v55, v52, v51
	v_cmp_lt_f32_e64 s[6:7], 0, v52
	v_sub_f32_e32 v39, v39, v53
	v_sub_f32_e32 v38, v38, v53
	v_cndmask_b32_e64 v52, v54, v55, s[6:7]
	v_mul_f32_e32 v54, 0x37800000, v52
	v_cndmask_b32_e32 v52, v52, v54, vcc
	v_cmp_class_f32_e32 vcc, v51, v198
	v_pk_fma_f32 v[10:11], v[26:27], v[10:11], v[42:43]
	v_pk_mul_f32 v[12:13], v[12:13], v[58:59] op_sel_hi:[1,0]
	v_cndmask_b32_e32 v51, v52, v51, vcc
	v_div_scale_f32 v52, s[0:1], v51, v51, 1.0
	v_rcp_f32_e32 v54, v52
	v_pk_fma_f32 v[12:13], v[28:29], v[12:13], v[44:45]
	v_fmac_f32_e32 v6, 0xba800000, v50
	v_pk_mul_f32 v[6:7], v[6:7], v[58:59] op_sel_hi:[1,0]
	v_fma_f32 v55, -v52, v54, 1.0
	v_fmac_f32_e32 v54, v55, v54
	v_div_scale_f32 v55, vcc, 1.0, v51, 1.0
	v_mul_f32_e32 v56, v55, v54
	v_fma_f32 v57, -v52, v56, v55
	v_fmac_f32_e32 v56, v57, v54
	v_fma_f32 v52, -v52, v56, v55
	v_div_fmas_f32 v52, v52, v54, v56
	v_div_fixup_f32 v52, v52, v51, 1.0
	v_pk_mul_f32 v[38:39], v[38:39], v[52:53] op_sel_hi:[1,0]
	v_pk_mul_f32 v[16:17], v[16:17], v[52:53] op_sel_hi:[1,0]
	v_pk_fma_f32 v[38:39], v[182:183], v[38:39], v[174:175]
	v_pk_fma_f32 v[16:17], v[160:161], v[16:17], v[176:177]
	v_add_u32_e32 v54, s26, v1
	v_cvt_pk_bf16_f32 v38, v38, v39
	v_cvt_pk_bf16_f32 v39, v16, v17
	v_cvt_pk_bf16_f32 v16, v10, v11
	v_sub_f32_e32 v11, v11, v53
	v_sub_f32_e32 v10, v10, v53
	v_ashrrev_i32_e32 v55, 31, v54
	v_pk_mul_f32 v[10:11], v[10:11], v[52:53] op_sel_hi:[1,0]
	v_lshlrev_b64 v[54:55], 11, v[54:55]
	v_pk_fma_f32 v[10:11], v[158:159], v[10:11], v[170:171]
	v_cvt_pk_bf16_f32 v17, v12, v13
	v_sub_f32_e32 v13, v13, v53
	v_sub_f32_e32 v12, v12, v53
	v_cvt_pk_bf16_f32 v40, v10, v11
	v_lshl_add_u64 v[10:11], s[84:85], 0, v[54:55]
	v_pk_mul_f32 v[12:13], v[12:13], v[52:53] op_sel_hi:[1,0]
	v_lshl_add_u64 v[26:27], v[10:11], 0, v[154:155]
	v_lshl_add_u64 v[10:11], s[66:67], 0, v[54:55]
	v_pk_mul_f32 v[8:9], v[8:9], v[58:59] op_sel_hi:[1,0]
	v_pk_fma_f32 v[12:13], v[156:157], v[12:13], v[172:173]
	v_pk_fma_f32 v[8:9], v[32:33], v[8:9], v[36:37]
	v_cvt_pk_bf16_f32 v41, v12, v13
	global_store_dwordx4 v[26:27], v[14:17], off
	v_fmamk_f32 v5, v50, 0xba800000, v5
	v_fmamk_f32 v4, v50, 0xba800000, v4
	v_lshl_add_u64 v[14:15], v[10:11], 0, v[154:155]
	v_pk_fma_f32 v[10:11], v[30:31], v[6:7], v[34:35]
	global_store_dwordx4 v[14:15], v[38:41], off
	v_cvt_pk_bf16_f32 v6, v10, v11
	v_cvt_pk_bf16_f32 v7, v8, v9
	v_sub_f32_e32 v9, v9, v53
	v_sub_f32_e32 v8, v8, v53
	v_sub_f32_e32 v11, v11, v53
	v_sub_f32_e32 v10, v10, v53
	v_fmamk_f32 v3, v50, 0xba800000, v3
	v_fmac_f32_e32 v2, 0xba800000, v50
	v_pk_mul_f32 v[10:11], v[10:11], v[52:53] op_sel_hi:[1,0]
	v_pk_mul_f32 v[8:9], v[8:9], v[52:53] op_sel_hi:[1,0]
	v_pk_mul_f32 v[2:3], v[2:3], v[58:59] op_sel_hi:[1,0]
	v_pk_mul_f32 v[4:5], v[4:5], v[58:59] op_sel_hi:[1,0]
	v_pk_fma_f32 v[8:9], v[150:151], v[8:9], v[168:169]
	v_pk_fma_f32 v[10:11], v[152:153], v[10:11], v[166:167]
	v_pk_fma_f32 v[4:5], v[20:21], v[4:5], v[24:25]
	v_pk_fma_f32 v[2:3], v[18:19], v[2:3], v[22:23]
	v_cvt_pk_bf16_f32 v10, v10, v11
	v_cvt_pk_bf16_f32 v11, v8, v9
	s_nop 0
	v_cvt_pk_bf16_f32 v8, v2, v3
	v_cvt_pk_bf16_f32 v9, v4, v5
	v_sub_f32_e32 v5, v5, v53
	v_sub_f32_e32 v4, v4, v53
	v_sub_f32_e32 v3, v3, v53
	v_sub_f32_e32 v2, v2, v53
	v_pk_mul_f32 v[2:3], v[2:3], v[52:53] op_sel_hi:[1,0]
	v_pk_mul_f32 v[4:5], v[4:5], v[52:53] op_sel_hi:[1,0]
	v_pk_fma_f32 v[2:3], v[148:149], v[2:3], v[162:163]
	v_pk_fma_f32 v[4:5], v[146:147], v[4:5], v[164:165]
	v_cvt_pk_bf16_f32 v12, v2, v3
	s_nop 0
	v_cvt_pk_bf16_f32 v13, v4, v5
	global_store_dwordx4 v[26:27], v[6:9], off offset:256
	global_store_dwordx4 v[14:15], v[10:13], off offset:256

.LBB0_694:
	s_or_b64 exec, exec, s[2:3]
	s_getpc_b64 s[100:101]
	v_mbcnt_lo_u32_b32 v244, -1, 0
	v_mbcnt_hi_u32_b32 v244, -1, v244
	v_lshlrev_b32_e32 v244, 7, v244
	v_min_u32_e32 v244, 0x780, v244
	global_load_dword v243, v244, s[100:101]
	s_waitcnt lgkmcnt(0)
	s_barrier
	v_lshl_add_u32 v162, v172, 3, 0
	ds_read_b64 v[164:165], v162 offset:8192
	v_add_u32_e32 v0, s99, v172
	v_ashrrev_i32_e32 v1, 31, v0
	v_lshlrev_b64 v[168:169], 12, v[0:1]
	v_lshl_add_u64 v[168:169], s[52:53], 0, v[168:169]
	s_waitcnt lgkmcnt(0)
	v_sub_f32_e32 v125, v125, v164
	v_sub_f32_e32 v124, v124, v164
	v_sub_f32_e32 v123, v123, v164
	v_sub_f32_e32 v122, v122, v164
	v_sub_f32_e32 v117, v117, v164
	v_sub_f32_e32 v116, v116, v164
	v_sub_f32_e32 v115, v115, v164
	v_sub_f32_e32 v114, v114, v164
	v_sub_f32_e32 v109, v109, v164
	v_sub_f32_e32 v108, v108, v164
	v_sub_f32_e32 v107, v107, v164
	v_sub_f32_e32 v106, v106, v164
	v_sub_f32_e32 v101, v101, v164
	v_sub_f32_e32 v100, v100, v164
	v_sub_f32_e32 v99, v99, v164
	v_sub_f32_e32 v98, v98, v164
	v_pk_mul_f32 v[122:123], v[164:165], v[122:123] op_sel:[1,0]
	v_pk_mul_f32 v[124:125], v[164:165], v[124:125] op_sel:[1,0]
	v_pk_mul_f32 v[114:115], v[164:165], v[114:115] op_sel:[1,0]
	v_pk_mul_f32 v[116:117], v[164:165], v[116:117] op_sel:[1,0]
	v_pk_mul_f32 v[106:107], v[164:165], v[106:107] op_sel:[1,0]
	v_pk_mul_f32 v[108:109], v[164:165], v[108:109] op_sel:[1,0]
	v_pk_mul_f32 v[98:99], v[164:165], v[98:99] op_sel:[1,0]
	v_pk_mul_f32 v[100:101], v[164:165], v[100:101] op_sel:[1,0]
	s_waitcnt vmcnt(2)
	v_pk_fma_f32 v[124:125], v[156:157], v[124:125], v[160:161]
	v_pk_fma_f32 v[122:123], v[154:155], v[122:123], v[158:159]
	v_lshl_add_u64 v[168:169], v[168:169], 0, v[166:167]
	v_pk_fma_f32 v[116:117], v[148:149], v[116:117], v[152:153]
	v_pk_fma_f32 v[114:115], v[146:147], v[114:115], v[150:151]
	s_waitcnt vmcnt(0)
	v_pk_fma_f32 v[108:109], v[140:141], v[108:109], v[144:145]
	v_pk_fma_f32 v[106:107], v[138:139], v[106:107], v[142:143]
	v_pk_fma_f32 v[100:101], v[132:133], v[100:101], v[136:137]
	v_pk_fma_f32 v[98:99], v[130:131], v[98:99], v[134:135]
	global_store_dwordx4 v[168:169], v[122:125], off
	global_store_dwordx4 v[168:169], v[114:117], off offset:16
	global_store_dwordx4 v[168:169], v[106:109], off offset:512
	global_store_dwordx4 v[168:169], v[98:101], off offset:528
	ds_read_b64 v[98:99], v162 offset:8320
	s_waitcnt lgkmcnt(0)
	v_sub_f32_e32 v81, v81, v98
	v_add_u32_e32 v100, 16, v0
	v_ashrrev_i32_e32 v101, 31, v100
	v_lshlrev_b64 v[100:101], 12, v[100:101]
	v_sub_f32_e32 v80, v80, v98
	v_sub_f32_e32 v79, v79, v98
	v_sub_f32_e32 v78, v78, v98
	v_sub_f32_e32 v85, v85, v98
	v_sub_f32_e32 v84, v84, v98
	v_sub_f32_e32 v83, v83, v98
	v_sub_f32_e32 v82, v82, v98
	v_lshl_add_u64 v[100:101], s[52:53], 0, v[100:101]
	v_pk_mul_f32 v[78:79], v[98:99], v[78:79] op_sel:[1,0]
	v_pk_mul_f32 v[80:81], v[98:99], v[80:81] op_sel:[1,0]
	v_pk_mul_f32 v[82:83], v[98:99], v[82:83] op_sel:[1,0]
	v_pk_mul_f32 v[84:85], v[98:99], v[84:85] op_sel:[1,0]
	v_lshl_add_u64 v[100:101], v[100:101], 0, v[166:167]
	v_pk_fma_f32 v[80:81], v[148:149], v[80:81], v[152:153]
	v_pk_fma_f32 v[78:79], v[146:147], v[78:79], v[150:151]
	v_pk_fma_f32 v[84:85], v[156:157], v[84:85], v[160:161]
	v_pk_fma_f32 v[82:83], v[154:155], v[82:83], v[158:159]
	global_store_dwordx4 v[100:101], v[78:81], off offset:16
	global_store_dwordx4 v[100:101], v[82:85], off
	s_nop 0
	v_sub_f32_e32 v79, v89, v98
	v_sub_f32_e32 v78, v88, v98
	v_sub_f32_e32 v81, v87, v98
	v_sub_f32_e32 v80, v86, v98
	v_pk_mul_f32 v[82:83], v[98:99], v[80:81] op_sel:[1,0]
	v_pk_mul_f32 v[78:79], v[98:99], v[78:79] op_sel:[1,0]
	s_nop 0
	v_pk_fma_f32 v[80:81], v[140:141], v[78:79], v[144:145]
	v_pk_fma_f32 v[78:79], v[138:139], v[82:83], v[142:143]
	global_store_dwordx4 v[100:101], v[78:81], off offset:512
	s_nop 1
	v_sub_f32_e32 v79, v93, v98
	v_sub_f32_e32 v78, v92, v98
	v_sub_f32_e32 v81, v91, v98
	v_sub_f32_e32 v80, v90, v98
	v_pk_mul_f32 v[82:83], v[98:99], v[80:81] op_sel:[1,0]
	v_pk_mul_f32 v[78:79], v[98:99], v[78:79] op_sel:[1,0]
	s_nop 0
	v_pk_fma_f32 v[80:81], v[132:133], v[78:79], v[136:137]
	v_pk_fma_f32 v[78:79], v[130:131], v[82:83], v[134:135]
	global_store_dwordx4 v[100:101], v[78:81], off offset:528
	ds_read_b64 v[82:83], v162 offset:8448
	s_nop 0
	v_add_u32_e32 v78, 32, v0
	v_ashrrev_i32_e32 v79, 31, v78
	v_lshlrev_b64 v[84:85], 12, v[78:79]
	s_waitcnt lgkmcnt(0)
	v_sub_f32_e32 v79, v129, v82
	v_sub_f32_e32 v78, v128, v82
	v_sub_f32_e32 v81, v127, v82
	v_sub_f32_e32 v80, v126, v82
	v_pk_mul_f32 v[86:87], v[82:83], v[80:81] op_sel:[1,0]
	v_pk_mul_f32 v[78:79], v[82:83], v[78:79] op_sel:[1,0]
	v_lshl_add_u64 v[84:85], s[52:53], 0, v[84:85]
	v_pk_fma_f32 v[80:81], v[156:157], v[78:79], v[160:161]
	v_pk_fma_f32 v[78:79], v[154:155], v[86:87], v[158:159]
	v_lshl_add_u64 v[84:85], v[84:85], 0, v[166:167]
	global_store_dwordx4 v[84:85], v[78:81], off
	s_nop 1
	v_sub_f32_e32 v79, v121, v82
	v_sub_f32_e32 v78, v120, v82
	v_sub_f32_e32 v81, v119, v82
	v_sub_f32_e32 v80, v118, v82
	v_pk_mul_f32 v[86:87], v[82:83], v[80:81] op_sel:[1,0]
	v_pk_mul_f32 v[78:79], v[82:83], v[78:79] op_sel:[1,0]
	s_nop 0
	v_pk_fma_f32 v[80:81], v[148:149], v[78:79], v[152:153]
	v_pk_fma_f32 v[78:79], v[146:147], v[86:87], v[150:151]
	global_store_dwordx4 v[84:85], v[78:81], off offset:16
	s_nop 1
	v_sub_f32_e32 v79, v113, v82
	v_sub_f32_e32 v78, v112, v82
	v_sub_f32_e32 v81, v111, v82
	v_sub_f32_e32 v80, v110, v82
	v_pk_mul_f32 v[86:87], v[82:83], v[80:81] op_sel:[1,0]
	v_pk_mul_f32 v[78:79], v[82:83], v[78:79] op_sel:[1,0]
	s_nop 0
	v_pk_fma_f32 v[80:81], v[140:141], v[78:79], v[144:145]
	v_pk_fma_f32 v[78:79], v[138:139], v[86:87], v[142:143]
	global_store_dwordx4 v[84:85], v[78:81], off offset:512
	s_nop 1
	v_sub_f32_e32 v79, v97, v82
	v_sub_f32_e32 v78, v96, v82
	v_sub_f32_e32 v81, v95, v82
	v_sub_f32_e32 v80, v94, v82
	v_pk_mul_f32 v[86:87], v[82:83], v[80:81] op_sel:[1,0]
	v_pk_mul_f32 v[78:79], v[82:83], v[78:79] op_sel:[1,0]
	s_nop 0
	v_pk_fma_f32 v[80:81], v[132:133], v[78:79], v[136:137]
	v_pk_fma_f32 v[78:79], v[130:131], v[86:87], v[134:135]
	global_store_dwordx4 v[84:85], v[78:81], off offset:528
	ds_read_b64 v[82:83], v162 offset:8576
	s_waitcnt lgkmcnt(0)
	v_sub_f32_e32 v77, v77, v82
	v_add_u32_e32 v78, 48, v0
	v_ashrrev_i32_e32 v79, 31, v78
	v_lshlrev_b64 v[84:85], 12, v[78:79]
	v_sub_f32_e32 v79, v105, v82
	v_sub_f32_e32 v78, v104, v82
	v_sub_f32_e32 v81, v103, v82
	v_sub_f32_e32 v80, v102, v82
	v_sub_f32_e32 v76, v76, v82
	v_sub_f32_e32 v75, v75, v82
	v_sub_f32_e32 v74, v74, v82
	v_sub_f32_e32 v73, v73, v82
	v_sub_f32_e32 v72, v72, v82
	v_sub_f32_e32 v71, v71, v82
	v_sub_f32_e32 v70, v70, v82
	v_sub_f32_e32 v69, v69, v82
	v_sub_f32_e32 v68, v68, v82
	v_sub_f32_e32 v67, v67, v82
	v_sub_f32_e32 v66, v66, v82
	v_pk_mul_f32 v[86:87], v[82:83], v[80:81] op_sel:[1,0]
	v_pk_mul_f32 v[78:79], v[82:83], v[78:79] op_sel:[1,0]
	v_lshl_add_u64 v[84:85], s[52:53], 0, v[84:85]
	v_pk_mul_f32 v[74:75], v[82:83], v[74:75] op_sel:[1,0]
	v_pk_mul_f32 v[76:77], v[82:83], v[76:77] op_sel:[1,0]
	v_pk_mul_f32 v[70:71], v[82:83], v[70:71] op_sel:[1,0]
	v_pk_mul_f32 v[72:73], v[82:83], v[72:73] op_sel:[1,0]
	v_pk_mul_f32 v[66:67], v[82:83], v[66:67] op_sel:[1,0]
	v_pk_mul_f32 v[68:69], v[82:83], v[68:69] op_sel:[1,0]
	v_pk_fma_f32 v[80:81], v[156:157], v[78:79], v[160:161]
	v_pk_fma_f32 v[78:79], v[154:155], v[86:87], v[158:159]
	v_lshl_add_u64 v[84:85], v[84:85], 0, v[166:167]
	v_pk_fma_f32 v[76:77], v[148:149], v[76:77], v[152:153]
	v_pk_fma_f32 v[74:75], v[146:147], v[74:75], v[150:151]
	v_pk_fma_f32 v[72:73], v[140:141], v[72:73], v[144:145]
	v_pk_fma_f32 v[70:71], v[138:139], v[70:71], v[142:143]
	v_pk_fma_f32 v[68:69], v[132:133], v[68:69], v[136:137]
	v_pk_fma_f32 v[66:67], v[130:131], v[66:67], v[134:135]
	ds_read_b64 v[66:67], v162 offset:9216
	s_waitcnt lgkmcnt(0)
	v_sub_f32_e32 v65, v65, v66
	v_add_u32_e32 v68, 0x60, v0
	v_ashrrev_i32_e32 v69, 31, v68
	v_lshlrev_b64 v[68:69], 12, v[68:69]
	v_sub_f32_e32 v64, v64, v66
	v_sub_f32_e32 v63, v63, v66
	v_sub_f32_e32 v62, v62, v66
	v_sub_f32_e32 v61, v61, v66
	v_sub_f32_e32 v60, v60, v66
	v_sub_f32_e32 v59, v59, v66
	v_sub_f32_e32 v58, v58, v66
	v_sub_f32_e32 v57, v57, v66
	v_sub_f32_e32 v56, v56, v66
	v_sub_f32_e32 v55, v55, v66
	v_sub_f32_e32 v54, v54, v66
	v_sub_f32_e32 v49, v49, v66
	v_sub_f32_e32 v48, v48, v66
	v_sub_f32_e32 v47, v47, v66
	v_sub_f32_e32 v46, v46, v66
	v_pk_mul_f32 v[62:63], v[66:67], v[62:63] op_sel:[1,0]
	v_pk_mul_f32 v[64:65], v[66:67], v[64:65] op_sel:[1,0]
	v_lshl_add_u64 v[68:69], s[52:53], 0, v[68:69]
	v_pk_mul_f32 v[58:59], v[66:67], v[58:59] op_sel:[1,0]
	v_pk_mul_f32 v[60:61], v[66:67], v[60:61] op_sel:[1,0]
	v_pk_mul_f32 v[54:55], v[66:67], v[54:55] op_sel:[1,0]
	v_pk_mul_f32 v[56:57], v[66:67], v[56:57] op_sel:[1,0]
	v_pk_mul_f32 v[46:47], v[66:67], v[46:47] op_sel:[1,0]
	v_pk_mul_f32 v[48:49], v[66:67], v[48:49] op_sel:[1,0]
	v_pk_fma_f32 v[64:65], v[156:157], v[64:65], v[160:161]
	v_pk_fma_f32 v[62:63], v[154:155], v[62:63], v[158:159]
	v_lshl_add_u64 v[68:69], v[68:69], 0, v[166:167]
	v_pk_fma_f32 v[60:61], v[148:149], v[60:61], v[152:153]
	v_pk_fma_f32 v[58:59], v[146:147], v[58:59], v[150:151]
	v_pk_fma_f32 v[56:57], v[140:141], v[56:57], v[144:145]
	v_pk_fma_f32 v[54:55], v[138:139], v[54:55], v[142:143]
	v_pk_fma_f32 v[48:49], v[132:133], v[48:49], v[136:137]
	v_pk_fma_f32 v[46:47], v[130:131], v[46:47], v[134:135]
	global_store_dwordx4 v[68:69], v[62:65], off
	global_store_dwordx4 v[68:69], v[58:61], off offset:16
	global_store_dwordx4 v[68:69], v[54:57], off offset:512
	global_store_dwordx4 v[68:69], v[46:49], off offset:528
	ds_read_b64 v[54:55], v162 offset:9344
	s_waitcnt lgkmcnt(0)
	v_sub_f32_e32 v45, v45, v54
	v_add_u32_e32 v46, 0x70, v0
	v_ashrrev_i32_e32 v47, 31, v46
	v_lshlrev_b64 v[56:57], 12, v[46:47]
	v_sub_f32_e32 v47, v53, v54
	v_sub_f32_e32 v46, v52, v54
	v_sub_f32_e32 v49, v51, v54
	v_sub_f32_e32 v48, v50, v54
	v_pk_mul_f32 v[50:51], v[54:55], v[48:49] op_sel:[1,0]
	v_pk_mul_f32 v[46:47], v[54:55], v[46:47] op_sel:[1,0]
	v_sub_f32_e32 v44, v44, v54
	v_sub_f32_e32 v43, v43, v54
	v_sub_f32_e32 v42, v42, v54
	v_sub_f32_e32 v41, v41, v54
	v_sub_f32_e32 v40, v40, v54
	v_sub_f32_e32 v39, v39, v54
	v_sub_f32_e32 v38, v38, v54
	v_sub_f32_e32 v33, v33, v54
	v_sub_f32_e32 v32, v32, v54
	v_sub_f32_e32 v31, v31, v54
	v_sub_f32_e32 v30, v30, v54
	v_pk_fma_f32 v[48:49], v[156:157], v[46:47], v[160:161]
	v_pk_fma_f32 v[46:47], v[154:155], v[50:51], v[158:159]
	v_lshl_add_u64 v[50:51], s[52:53], 0, v[56:57]
	v_pk_mul_f32 v[42:43], v[54:55], v[42:43] op_sel:[1,0]
	v_pk_mul_f32 v[44:45], v[54:55], v[44:45] op_sel:[1,0]
	v_pk_mul_f32 v[38:39], v[54:55], v[38:39] op_sel:[1,0]
	v_pk_mul_f32 v[40:41], v[54:55], v[40:41] op_sel:[1,0]
	v_pk_mul_f32 v[30:31], v[54:55], v[30:31] op_sel:[1,0]
	v_pk_mul_f32 v[32:33], v[54:55], v[32:33] op_sel:[1,0]
	v_lshl_add_u64 v[50:51], v[50:51], 0, v[166:167]
	v_pk_fma_f32 v[44:45], v[148:149], v[44:45], v[152:153]
	v_pk_fma_f32 v[42:43], v[146:147], v[42:43], v[150:151]
	v_pk_fma_f32 v[40:41], v[140:141], v[40:41], v[144:145]
	v_pk_fma_f32 v[38:39], v[138:139], v[38:39], v[142:143]
	v_pk_fma_f32 v[32:33], v[132:133], v[32:33], v[136:137]
	v_pk_fma_f32 v[30:31], v[130:131], v[30:31], v[134:135]
	global_store_dwordx4 v[50:51], v[46:49], off
	global_store_dwordx4 v[50:51], v[42:45], off offset:16
	global_store_dwordx4 v[50:51], v[38:41], off offset:512
	global_store_dwordx4 v[50:51], v[30:33], off offset:528
	ds_read_b64 v[38:39], v162 offset:9472
	s_waitcnt lgkmcnt(0)
	v_sub_f32_e32 v29, v29, v38
	v_add_u32_e32 v30, 0x80, v0
	v_ashrrev_i32_e32 v31, 31, v30
	v_lshlrev_b64 v[40:41], 12, v[30:31]
	v_sub_f32_e32 v31, v37, v38
	v_sub_f32_e32 v30, v36, v38
	v_sub_f32_e32 v33, v35, v38
	v_sub_f32_e32 v32, v34, v38
	v_pk_mul_f32 v[34:35], v[38:39], v[32:33] op_sel:[1,0]
	v_pk_mul_f32 v[30:31], v[38:39], v[30:31] op_sel:[1,0]
	v_sub_f32_e32 v28, v28, v38
	v_sub_f32_e32 v27, v27, v38
	v_sub_f32_e32 v26, v26, v38
	v_sub_f32_e32 v25, v25, v38
	v_sub_f32_e32 v24, v24, v38
	v_sub_f32_e32 v23, v23, v38
	v_sub_f32_e32 v22, v22, v38
	v_sub_f32_e32 v17, v17, v38
	v_sub_f32_e32 v16, v16, v38
	v_sub_f32_e32 v15, v15, v38
	v_sub_f32_e32 v14, v14, v38
	v_pk_fma_f32 v[32:33], v[156:157], v[30:31], v[160:161]
	v_pk_fma_f32 v[30:31], v[154:155], v[34:35], v[158:159]
	v_lshl_add_u64 v[34:35], s[52:53], 0, v[40:41]
	v_pk_mul_f32 v[26:27], v[38:39], v[26:27] op_sel:[1,0]
	v_pk_mul_f32 v[28:29], v[38:39], v[28:29] op_sel:[1,0]
	v_pk_mul_f32 v[22:23], v[38:39], v[22:23] op_sel:[1,0]
	v_pk_mul_f32 v[24:25], v[38:39], v[24:25] op_sel:[1,0]
	v_pk_mul_f32 v[14:15], v[38:39], v[14:15] op_sel:[1,0]
	v_pk_mul_f32 v[16:17], v[38:39], v[16:17] op_sel:[1,0]
	v_lshl_add_u64 v[34:35], v[34:35], 0, v[166:167]
	v_pk_fma_f32 v[28:29], v[148:149], v[28:29], v[152:153]
	v_pk_fma_f32 v[26:27], v[146:147], v[26:27], v[150:151]
	v_pk_fma_f32 v[24:25], v[140:141], v[24:25], v[144:145]
	v_pk_fma_f32 v[22:23], v[138:139], v[22:23], v[142:143]
	v_pk_fma_f32 v[16:17], v[132:133], v[16:17], v[136:137]
	v_pk_fma_f32 v[14:15], v[130:131], v[14:15], v[134:135]
	global_store_dwordx4 v[34:35], v[30:33], off
	global_store_dwordx4 v[34:35], v[26:29], off offset:16
	global_store_dwordx4 v[34:35], v[22:25], off offset:512
	global_store_dwordx4 v[34:35], v[14:17], off offset:528
	ds_read_b64 v[22:23], v162 offset:9600
	v_add_u32_e32 v0, 0xb0, v0
	v_ashrrev_i32_e32 v1, 31, v0
	v_lshlrev_b64 v[0:1], 12, v[0:1]
	v_lshl_add_u64 v[0:1], s[52:53], 0, v[0:1]
	s_waitcnt lgkmcnt(0)
	v_sub_f32_e32 v15, v21, v22
	v_sub_f32_e32 v14, v20, v22
	v_sub_f32_e32 v17, v19, v22
	v_sub_f32_e32 v16, v18, v22
	v_pk_mul_f32 v[18:19], v[22:23], v[16:17] op_sel:[1,0]
	v_pk_mul_f32 v[14:15], v[22:23], v[14:15] op_sel:[1,0]
	v_sub_f32_e32 v11, v11, v22
	v_pk_fma_f32 v[16:17], v[156:157], v[14:15], v[160:161]
	v_pk_fma_f32 v[14:15], v[154:155], v[18:19], v[158:159]
	v_lshl_add_u64 v[18:19], v[0:1], 0, v[166:167]
	v_sub_f32_e32 v1, v13, v22
	v_sub_f32_e32 v0, v12, v22
	v_pk_mul_f32 v[0:1], v[22:23], v[0:1] op_sel:[1,0]
	v_sub_f32_e32 v10, v10, v22
	v_pk_fma_f32 v[12:13], v[148:149], v[0:1], v[152:153]
	v_sub_f32_e32 v1, v9, v22
	v_sub_f32_e32 v0, v8, v22
	v_pk_mul_f32 v[0:1], v[22:23], v[0:1] op_sel:[1,0]
	v_sub_f32_e32 v7, v7, v22
	v_sub_f32_e32 v6, v6, v22
	v_pk_fma_f32 v[8:9], v[140:141], v[0:1], v[144:145]
	v_sub_f32_e32 v1, v5, v22
	v_sub_f32_e32 v0, v4, v22
	v_sub_f32_e32 v3, v3, v22
	v_sub_f32_e32 v2, v2, v22
	v_pk_mul_f32 v[10:11], v[22:23], v[10:11] op_sel:[1,0]
	v_pk_mul_f32 v[6:7], v[22:23], v[6:7] op_sel:[1,0]
	v_pk_mul_f32 v[4:5], v[22:23], v[2:3] op_sel:[1,0]
	v_pk_mul_f32 v[0:1], v[22:23], v[0:1] op_sel:[1,0]
	v_pk_fma_f32 v[10:11], v[146:147], v[10:11], v[150:151]
	v_pk_fma_f32 v[6:7], v[138:139], v[6:7], v[142:143]
	v_pk_fma_f32 v[2:3], v[132:133], v[0:1], v[136:137]
	v_pk_fma_f32 v[0:1], v[130:131], v[4:5], v[134:135]

	.amdhsa_kernel _Z10fwd_kernel4Args
		.amdhsa_group_segment_fixed_size 0
		.amdhsa_private_segment_fixed_size 0
		.amdhsa_kernarg_size 512
		.amdhsa_user_sgpr_count 2
		.amdhsa_user_sgpr_dispatch_ptr 0
		.amdhsa_user_sgpr_queue_ptr 0
		.amdhsa_user_sgpr_kernarg_segment_ptr 1
		.amdhsa_user_sgpr_dispatch_id 0
		.amdhsa_user_sgpr_kernarg_preload_length 0
		.amdhsa_user_sgpr_kernarg_preload_offset 0
		.amdhsa_user_sgpr_private_segment_size 0
		.amdhsa_uses_dynamic_stack 0
		.amdhsa_enable_private_segment 0
		.amdhsa_system_sgpr_workgroup_id_x 1
		.amdhsa_system_sgpr_workgroup_id_y 0
		.amdhsa_system_sgpr_workgroup_id_z 0
		.amdhsa_system_sgpr_workgroup_info 0
		.amdhsa_system_vgpr_workitem_id 0
		.amdhsa_next_free_vgpr 245
		.amdhsa_next_free_sgpr 102
		.amdhsa_accum_offset 248
		.amdhsa_reserve_vcc 1
		.amdhsa_float_round_mode_32 0
		.amdhsa_float_round_mode_16_64 0
		.amdhsa_float_denorm_mode_32 3
		.amdhsa_float_denorm_mode_16_64 3
		.amdhsa_dx10_clamp 1
		.amdhsa_ieee_mode 1
		.amdhsa_fp16_overflow 0
		.amdhsa_tg_split 0
		.amdhsa_exception_fp_ieee_invalid_op 0
		.amdhsa_exception_fp_denorm_src 0
		.amdhsa_exception_fp_ieee_div_zero 0
		.amdhsa_exception_fp_ieee_overflow 0
		.amdhsa_exception_fp_ieee_underflow 0
		.amdhsa_exception_fp_ieee_inexact 0
		.amdhsa_exception_int_div_zero 0
	.end_amdhsa_kernel

amdhsa.kernels:
  - .agpr_count:     0
    .args:
      - .offset:         0
        .size:           256
        .value_kind:     by_value
      - .offset:         256
        .size:           4
        .value_kind:     hidden_block_count_x
      - .offset:         260
        .size:           4
        .value_kind:     hidden_block_count_y
      - .offset:         264
        .size:           4
        .value_kind:     hidden_block_count_z
      - .offset:         268
        .size:           2
        .value_kind:     hidden_group_size_x
      - .offset:         270
        .size:           2
        .value_kind:     hidden_group_size_y
      - .offset:         272
        .size:           2
        .value_kind:     hidden_group_size_z
      - .offset:         274
        .size:           2
        .value_kind:     hidden_remainder_x
      - .offset:         276
        .size:           2
        .value_kind:     hidden_remainder_y
      - .offset:         278
        .size:           2
        .value_kind:     hidden_remainder_z
      - .offset:         296
        .size:           8
        .value_kind:     hidden_global_offset_x
      - .offset:         304
        .size:           8
        .value_kind:     hidden_global_offset_y
      - .offset:         312
        .size:           8
        .value_kind:     hidden_global_offset_z
      - .offset:         320
        .size:           2
        .value_kind:     hidden_grid_dims
      - .offset:         376
        .size:           4
        .value_kind:     hidden_dynamic_lds_size
    .group_segment_fixed_size: 0
    .kernarg_segment_align: 8
    .kernarg_segment_size: 512
    .language:       OpenCL C
    .language_version:
      - 2
      - 0
    .max_flat_workgroup_size: 512
    .name:           _Z10fwd_kernel4Args
    .private_segment_fixed_size: 0
    .sgpr_count:     108
    .sgpr_spill_count: 42
    .symbol:         _Z10fwd_kernel4Args.kd
    .uniform_work_group_size: 1
    .uses_dynamic_stack: false
    .vgpr_count:     245
    .vgpr_spill_count: 0
    .wavefront_size: 64
